# GEMM K-loops: one counted vmcnt(10) wait per phase covering only the stage read next, instead of two vmcnt(6) per iteration (stages may stay in flight 5 phases instead of 3)
# baseline (speedup 1.0000x reference)
.LBB0_133:
	s_add_u32 s28, s22, 0x100
	s_addc_u32 s29, s23, 0
	s_add_i32 s85, 0, 0x10000
	v_add_u32_e32 v148, s85, v157
	ds_read_b128 v[130:133], v148
	ds_read_b128 v[134:137], v148 offset:1024
	ds_read_b128 v[138:141], v148 offset:2048
	ds_read_b128 v[148:151], v148 offset:3072
	s_cmp_eq_u32 s84, 40
	s_cselect_b32 s43, s17, s29
	s_cselect_b32 s42, s16, s28
	s_cselect_b32 s41, s19, s79
	s_cselect_b32 s40, s18, s34
	v_lshl_add_u64 v[188:189], s[22:23], 0, v[146:147]
	s_add_i32 m0, s54, 0xc000
	ds_read_b128 v[152:155], v159
	ds_read_b128 v[160:163], v159 offset:1024
	ds_read_b128 v[164:167], v159 offset:2048
	ds_read_b128 v[168:171], v159 offset:3072
	ds_read_b128 v[172:175], v159 offset:4096
	ds_read_b128 v[176:179], v159 offset:5120
	ds_read_b128 v[180:183], v159 offset:6144
	ds_read_b128 v[184:187], v159 offset:7168
	global_load_lds_dwordx4 v[188:189], off
	v_lshl_add_u64 v[188:189], s[22:23], 0, v[144:145]
	s_add_i32 m0, s54, 0xe000
	s_nop 0
	global_load_lds_dwordx4 v[188:189], off
	s_waitcnt lgkmcnt(8)
	s_waitcnt vmcnt(10)
	s_barrier
	s_waitcnt lgkmcnt(0)
	s_waitcnt lgkmcnt(0)
	v_mfma_f32_16x16x32_bf16 v[126:129], v[130:133], v[152:155], v[126:129]
	v_mfma_f32_16x16x32_bf16 v[122:125], v[138:141], v[152:155], v[122:125]
	v_mfma_f32_16x16x32_bf16 v[118:121], v[130:133], v[164:167], v[118:121]
	v_mfma_f32_16x16x32_bf16 v[106:109], v[138:141], v[164:167], v[106:109]
	v_mfma_f32_16x16x32_bf16 v[102:105], v[130:133], v[172:175], v[102:105]
	v_mfma_f32_16x16x32_bf16 v[90:93], v[138:141], v[172:175], v[90:93]
	v_mfma_f32_16x16x32_bf16 v[86:89], v[130:133], v[180:183], v[86:89]
	v_mfma_f32_16x16x32_bf16 v[74:77], v[138:141], v[180:183], v[74:77]
	v_mfma_f32_16x16x32_bf16 v[126:129], v[134:137], v[160:163], v[126:129]
	v_mfma_f32_16x16x32_bf16 v[122:125], v[148:151], v[160:163], v[122:125]
	v_mfma_f32_16x16x32_bf16 v[118:121], v[134:137], v[168:171], v[118:121]
	v_mfma_f32_16x16x32_bf16 v[106:109], v[148:151], v[168:171], v[106:109]
	v_mfma_f32_16x16x32_bf16 v[102:105], v[134:137], v[176:179], v[102:105]
	v_mfma_f32_16x16x32_bf16 v[90:93], v[148:151], v[176:179], v[90:93]
	v_mfma_f32_16x16x32_bf16 v[86:89], v[134:137], v[184:187], v[86:89]
	v_mfma_f32_16x16x32_bf16 v[74:77], v[148:151], v[184:187], v[74:77]
	s_barrier
	s_add_i32 s86, 0, 0x14000
	v_add_u32_e32 v196, s86, v157
	s_add_i32 s22, s85, s50
	ds_read_b128 v[188:191], v196
	ds_read_b128 v[192:195], v196 offset:1024
	ds_read_b128 v[208:211], v196 offset:2048
	ds_read_b128 v[212:215], v196 offset:3072
	v_lshl_add_u64 v[196:197], s[40:41], 0, v[16:17]
	s_mov_b32 m0, s22
	v_lshl_add_u64 v[216:217], s[40:41], 0, v[142:143]
	global_load_lds_dwordx4 v[196:197], off
	s_add_i32 m0, s22, 0x2000
	s_nop 0
	global_load_lds_dwordx4 v[216:217], off
	s_waitcnt vmcnt(10)
	s_barrier
	s_waitcnt lgkmcnt(0)
	s_waitcnt lgkmcnt(0)
	v_mfma_f32_16x16x32_bf16 v[114:117], v[188:191], v[152:155], v[114:117]
	v_mfma_f32_16x16x32_bf16 v[110:113], v[208:211], v[152:155], v[110:113]
	v_mfma_f32_16x16x32_bf16 v[98:101], v[188:191], v[164:167], v[98:101]
	v_mfma_f32_16x16x32_bf16 v[94:97], v[208:211], v[164:167], v[94:97]
	v_mfma_f32_16x16x32_bf16 v[82:85], v[188:191], v[172:175], v[82:85]
	v_mfma_f32_16x16x32_bf16 v[78:81], v[208:211], v[172:175], v[78:81]
	v_mfma_f32_16x16x32_bf16 v[70:73], v[188:191], v[180:183], v[70:73]
	v_mfma_f32_16x16x32_bf16 v[66:69], v[208:211], v[180:183], v[66:69]
	v_mfma_f32_16x16x32_bf16 v[114:117], v[192:195], v[160:163], v[114:117]
	v_mfma_f32_16x16x32_bf16 v[110:113], v[212:215], v[160:163], v[110:113]
	v_mfma_f32_16x16x32_bf16 v[98:101], v[192:195], v[168:171], v[98:101]
	v_mfma_f32_16x16x32_bf16 v[94:97], v[212:215], v[168:171], v[94:97]
	v_mfma_f32_16x16x32_bf16 v[82:85], v[192:195], v[176:179], v[82:85]
	v_mfma_f32_16x16x32_bf16 v[78:81], v[212:215], v[176:179], v[78:81]
	v_mfma_f32_16x16x32_bf16 v[70:73], v[192:195], v[184:187], v[70:73]
	v_mfma_f32_16x16x32_bf16 v[66:69], v[212:215], v[184:187], v[66:69]
	s_mov_b32 m0, s54
	v_lshl_add_u64 v[218:219], s[42:43], 0, v[16:17]
	s_barrier
	ds_read_b128 v[152:155], v159 offset:16384
	ds_read_b128 v[160:163], v159 offset:17408
	ds_read_b128 v[164:167], v159 offset:18432
	ds_read_b128 v[168:171], v159 offset:19456
	ds_read_b128 v[172:175], v159 offset:20480
	ds_read_b128 v[176:179], v159 offset:21504
	ds_read_b128 v[180:183], v159 offset:22528
	ds_read_b128 v[184:187], v159 offset:23552
	global_load_lds_dwordx4 v[218:219], off
	v_lshl_add_u64 v[220:221], s[42:43], 0, v[142:143]
	s_mov_b32 m0, s55
	s_nop 0
	global_load_lds_dwordx4 v[220:221], off
	s_barrier
	s_waitcnt lgkmcnt(0)
	s_waitcnt lgkmcnt(0)
	v_mfma_f32_16x16x32_bf16 v[62:65], v[130:133], v[152:155], v[62:65]
	v_mfma_f32_16x16x32_bf16 v[58:61], v[138:141], v[152:155], v[58:61]
	v_mfma_f32_16x16x32_bf16 v[54:57], v[130:133], v[164:167], v[54:57]
	v_mfma_f32_16x16x32_bf16 v[50:53], v[138:141], v[164:167], v[50:53]
	v_mfma_f32_16x16x32_bf16 v[46:49], v[130:133], v[172:175], v[46:49]
	v_mfma_f32_16x16x32_bf16 v[38:41], v[138:141], v[172:175], v[38:41]
	v_mfma_f32_16x16x32_bf16 v[30:33], v[130:133], v[180:183], v[30:33]
	v_mfma_f32_16x16x32_bf16 v[18:21], v[138:141], v[180:183], v[18:21]
	v_mfma_f32_16x16x32_bf16 v[62:65], v[134:137], v[160:163], v[62:65]
	v_mfma_f32_16x16x32_bf16 v[58:61], v[148:151], v[160:163], v[58:61]
	v_mfma_f32_16x16x32_bf16 v[54:57], v[134:137], v[168:171], v[54:57]
	v_mfma_f32_16x16x32_bf16 v[50:53], v[148:151], v[168:171], v[50:53]
	v_mfma_f32_16x16x32_bf16 v[46:49], v[134:137], v[176:179], v[46:49]
	v_mfma_f32_16x16x32_bf16 v[38:41], v[148:151], v[176:179], v[38:41]
	v_mfma_f32_16x16x32_bf16 v[30:33], v[134:137], v[184:187], v[30:33]
	v_mfma_f32_16x16x32_bf16 v[18:21], v[148:151], v[184:187], v[18:21]
	s_barrier
	s_add_u32 s22, s40, 0xb0000
	s_addc_u32 s23, s41, 0
	s_add_i32 s85, s86, s50
	v_lshl_add_u64 v[130:131], s[22:23], 0, v[16:17]
	s_mov_b32 m0, s85
	s_nop 0
	global_load_lds_dwordx4 v[130:131], off
	v_lshl_add_u64 v[130:131], s[22:23], 0, v[142:143]
	s_add_i32 m0, s85, 0x2000
	s_nop 0
	global_load_lds_dwordx4 v[130:131], off
	s_waitcnt vmcnt(10)
	s_barrier
	v_mfma_f32_16x16x32_bf16 v[42:45], v[188:191], v[152:155], v[42:45]
	v_mfma_f32_16x16x32_bf16 v[34:37], v[208:211], v[152:155], v[34:37]
	v_mfma_f32_16x16x32_bf16 v[26:29], v[188:191], v[164:167], v[26:29]
	v_mfma_f32_16x16x32_bf16 v[22:25], v[208:211], v[164:167], v[22:25]
	v_mfma_f32_16x16x32_bf16 v[12:15], v[188:191], v[172:175], v[12:15]
	v_mfma_f32_16x16x32_bf16 v[8:11], v[208:211], v[172:175], v[8:11]
	v_mfma_f32_16x16x32_bf16 v[4:7], v[188:191], v[180:183], v[4:7]
	v_mfma_f32_16x16x32_bf16 v[0:3], v[208:211], v[180:183], v[0:3]
	v_mfma_f32_16x16x32_bf16 v[42:45], v[192:195], v[160:163], v[42:45]
	v_mfma_f32_16x16x32_bf16 v[34:37], v[212:215], v[160:163], v[34:37]
	v_mfma_f32_16x16x32_bf16 v[26:29], v[192:195], v[168:171], v[26:29]
	v_mfma_f32_16x16x32_bf16 v[22:25], v[212:215], v[168:171], v[22:25]
	v_mfma_f32_16x16x32_bf16 v[12:15], v[192:195], v[176:179], v[12:15]
	v_mfma_f32_16x16x32_bf16 v[8:11], v[212:215], v[176:179], v[8:11]
	v_mfma_f32_16x16x32_bf16 v[4:7], v[192:195], v[184:187], v[4:7]
	v_mfma_f32_16x16x32_bf16 v[0:3], v[212:215], v[184:187], v[0:3]
	s_add_i32 s85, 0, 0x18000
	v_add_u32_e32 v148, s85, v157
	s_barrier
	ds_read_b128 v[130:133], v148
	ds_read_b128 v[134:137], v148 offset:1024
	ds_read_b128 v[138:141], v148 offset:2048
	ds_read_b128 v[148:151], v148 offset:3072
	s_add_u32 s22, s42, 0xb0000
	s_addc_u32 s23, s43, 0
	s_mov_b32 m0, s56
	v_lshl_add_u64 v[188:189], s[22:23], 0, v[16:17]
	ds_read_b128 v[152:155], v159 offset:32768
	ds_read_b128 v[160:163], v159 offset:33792
	ds_read_b128 v[164:167], v159 offset:34816
	ds_read_b128 v[168:171], v159 offset:35840
	ds_read_b128 v[172:175], v159 offset:36864
	ds_read_b128 v[176:179], v159 offset:37888
	ds_read_b128 v[180:183], v159 offset:38912
	ds_read_b128 v[184:187], v159 offset:39936
	global_load_lds_dwordx4 v[188:189], off
	v_lshl_add_u64 v[188:189], s[22:23], 0, v[142:143]
	s_mov_b32 m0, s57
	s_nop 0
	global_load_lds_dwordx4 v[188:189], off
	s_waitcnt lgkmcnt(8)
	s_waitcnt vmcnt(10)
	s_barrier
	s_waitcnt lgkmcnt(0)
	s_waitcnt lgkmcnt(0)
	v_mfma_f32_16x16x32_bf16 v[126:129], v[130:133], v[152:155], v[126:129]
	v_mfma_f32_16x16x32_bf16 v[122:125], v[138:141], v[152:155], v[122:125]
	v_mfma_f32_16x16x32_bf16 v[118:121], v[130:133], v[164:167], v[118:121]
	v_mfma_f32_16x16x32_bf16 v[106:109], v[138:141], v[164:167], v[106:109]
	v_mfma_f32_16x16x32_bf16 v[102:105], v[130:133], v[172:175], v[102:105]
	v_mfma_f32_16x16x32_bf16 v[90:93], v[138:141], v[172:175], v[90:93]
	v_mfma_f32_16x16x32_bf16 v[86:89], v[130:133], v[180:183], v[86:89]
	v_mfma_f32_16x16x32_bf16 v[74:77], v[138:141], v[180:183], v[74:77]
	v_mfma_f32_16x16x32_bf16 v[126:129], v[134:137], v[160:163], v[126:129]
	v_mfma_f32_16x16x32_bf16 v[122:125], v[148:151], v[160:163], v[122:125]
	v_mfma_f32_16x16x32_bf16 v[118:121], v[134:137], v[168:171], v[118:121]
	v_mfma_f32_16x16x32_bf16 v[106:109], v[148:151], v[168:171], v[106:109]
	v_mfma_f32_16x16x32_bf16 v[102:105], v[134:137], v[176:179], v[102:105]
	v_mfma_f32_16x16x32_bf16 v[90:93], v[148:151], v[176:179], v[90:93]
	v_mfma_f32_16x16x32_bf16 v[86:89], v[134:137], v[184:187], v[86:89]
	v_mfma_f32_16x16x32_bf16 v[74:77], v[148:151], v[184:187], v[74:77]
	s_barrier
	s_add_i32 s42, 0, 0x1c000
	s_add_i32 s22, s85, s50
	v_add_u32_e32 v212, s42, v157
	v_lshl_add_u64 v[196:197], v[196:197], 0, s[10:11]
	s_mov_b32 m0, s22
	ds_read_b128 v[188:191], v212
	ds_read_b128 v[192:195], v212 offset:1024
	ds_read_b128 v[208:211], v212 offset:2048
	ds_read_b128 v[212:215], v212 offset:3072
	global_load_lds_dwordx4 v[196:197], off
	v_lshl_add_u64 v[196:197], v[216:217], 0, s[10:11]
	s_add_i32 m0, s22, 0x2000
	s_nop 0
	global_load_lds_dwordx4 v[196:197], off
	s_waitcnt vmcnt(10)
	s_barrier
	s_waitcnt lgkmcnt(0)
	s_waitcnt lgkmcnt(0)
	v_mfma_f32_16x16x32_bf16 v[114:117], v[188:191], v[152:155], v[114:117]
	v_mfma_f32_16x16x32_bf16 v[110:113], v[208:211], v[152:155], v[110:113]
	v_mfma_f32_16x16x32_bf16 v[98:101], v[188:191], v[164:167], v[98:101]
	v_mfma_f32_16x16x32_bf16 v[94:97], v[208:211], v[164:167], v[94:97]
	v_mfma_f32_16x16x32_bf16 v[82:85], v[188:191], v[172:175], v[82:85]
	v_mfma_f32_16x16x32_bf16 v[78:81], v[208:211], v[172:175], v[78:81]
	v_mfma_f32_16x16x32_bf16 v[70:73], v[188:191], v[180:183], v[70:73]
	v_mfma_f32_16x16x32_bf16 v[66:69], v[208:211], v[180:183], v[66:69]
	v_mfma_f32_16x16x32_bf16 v[114:117], v[192:195], v[160:163], v[114:117]
	v_mfma_f32_16x16x32_bf16 v[110:113], v[212:215], v[160:163], v[110:113]
	v_mfma_f32_16x16x32_bf16 v[98:101], v[192:195], v[168:171], v[98:101]
	v_mfma_f32_16x16x32_bf16 v[94:97], v[212:215], v[168:171], v[94:97]
	v_mfma_f32_16x16x32_bf16 v[82:85], v[192:195], v[176:179], v[82:85]
	v_mfma_f32_16x16x32_bf16 v[78:81], v[212:215], v[176:179], v[78:81]
	v_mfma_f32_16x16x32_bf16 v[70:73], v[192:195], v[184:187], v[70:73]
	v_mfma_f32_16x16x32_bf16 v[66:69], v[212:215], v[184:187], v[66:69]
	s_mov_b32 m0, s58
	v_lshl_add_u64 v[196:197], v[218:219], 0, s[10:11]
	s_barrier
	ds_read_b128 v[152:155], v159 offset:49152
	ds_read_b128 v[160:163], v159 offset:50176
	ds_read_b128 v[164:167], v159 offset:51200
	ds_read_b128 v[168:171], v159 offset:52224
	ds_read_b128 v[172:175], v159 offset:53248
	ds_read_b128 v[176:179], v159 offset:54272
	ds_read_b128 v[180:183], v159 offset:55296
	ds_read_b128 v[184:187], v159 offset:56320
	global_load_lds_dwordx4 v[196:197], off
	v_lshl_add_u64 v[196:197], v[220:221], 0, s[10:11]
	s_mov_b32 m0, s59
	s_nop 0
	global_load_lds_dwordx4 v[196:197], off
	s_barrier
	s_waitcnt lgkmcnt(0)
	s_waitcnt lgkmcnt(0)
	v_mfma_f32_16x16x32_bf16 v[62:65], v[130:133], v[152:155], v[62:65]
	v_mfma_f32_16x16x32_bf16 v[58:61], v[138:141], v[152:155], v[58:61]
	v_mfma_f32_16x16x32_bf16 v[54:57], v[130:133], v[164:167], v[54:57]
	v_mfma_f32_16x16x32_bf16 v[50:53], v[138:141], v[164:167], v[50:53]
	v_mfma_f32_16x16x32_bf16 v[46:49], v[130:133], v[172:175], v[46:49]
	v_mfma_f32_16x16x32_bf16 v[38:41], v[138:141], v[172:175], v[38:41]
	v_mfma_f32_16x16x32_bf16 v[30:33], v[130:133], v[180:183], v[30:33]
	v_mfma_f32_16x16x32_bf16 v[18:21], v[138:141], v[180:183], v[18:21]
	v_mfma_f32_16x16x32_bf16 v[62:65], v[134:137], v[160:163], v[62:65]
	v_mfma_f32_16x16x32_bf16 v[58:61], v[148:151], v[160:163], v[58:61]
	v_mfma_f32_16x16x32_bf16 v[54:57], v[134:137], v[168:171], v[54:57]
	v_mfma_f32_16x16x32_bf16 v[50:53], v[148:151], v[168:171], v[50:53]
	v_mfma_f32_16x16x32_bf16 v[46:49], v[134:137], v[176:179], v[46:49]
	v_mfma_f32_16x16x32_bf16 v[38:41], v[148:151], v[176:179], v[38:41]
	v_mfma_f32_16x16x32_bf16 v[30:33], v[134:137], v[184:187], v[30:33]
	v_mfma_f32_16x16x32_bf16 v[18:21], v[148:151], v[184:187], v[18:21]
	s_barrier
	s_add_u32 s22, s40, 0xb0080
	s_addc_u32 s23, s41, 0
	s_add_i32 s40, s42, s50
	v_lshl_add_u64 v[130:131], s[22:23], 0, v[16:17]
	s_mov_b32 m0, s40
	s_nop 0
	global_load_lds_dwordx4 v[130:131], off
	v_lshl_add_u64 v[130:131], s[22:23], 0, v[142:143]
	s_add_i32 m0, s40, 0x2000
	s_nop 0
	global_load_lds_dwordx4 v[130:131], off
	s_waitcnt vmcnt(10)
	s_barrier
	v_mfma_f32_16x16x32_bf16 v[42:45], v[188:191], v[152:155], v[42:45]
	v_mfma_f32_16x16x32_bf16 v[34:37], v[208:211], v[152:155], v[34:37]
	v_mfma_f32_16x16x32_bf16 v[26:29], v[188:191], v[164:167], v[26:29]
	v_mfma_f32_16x16x32_bf16 v[22:25], v[208:211], v[164:167], v[22:25]
	v_mfma_f32_16x16x32_bf16 v[12:15], v[188:191], v[172:175], v[12:15]
	v_mfma_f32_16x16x32_bf16 v[8:11], v[208:211], v[172:175], v[8:11]
	v_mfma_f32_16x16x32_bf16 v[4:7], v[188:191], v[180:183], v[4:7]
	v_mfma_f32_16x16x32_bf16 v[0:3], v[208:211], v[180:183], v[0:3]
	v_mfma_f32_16x16x32_bf16 v[42:45], v[192:195], v[160:163], v[42:45]
	v_mfma_f32_16x16x32_bf16 v[34:37], v[212:215], v[160:163], v[34:37]
	v_mfma_f32_16x16x32_bf16 v[26:29], v[192:195], v[168:171], v[26:29]
	v_mfma_f32_16x16x32_bf16 v[22:25], v[212:215], v[168:171], v[22:25]
	v_mfma_f32_16x16x32_bf16 v[12:15], v[192:195], v[176:179], v[12:15]
	v_mfma_f32_16x16x32_bf16 v[8:11], v[212:215], v[176:179], v[8:11]
	v_mfma_f32_16x16x32_bf16 v[4:7], v[192:195], v[184:187], v[4:7]
	v_mfma_f32_16x16x32_bf16 v[0:3], v[212:215], v[184:187], v[0:3]
	s_add_i32 s84, s84, 2
	s_add_u32 s34, s34, 0x100
	s_addc_u32 s79, s79, 0
	s_cmp_gt_u32 s84, 41
	s_mov_b64 s[22:23], s[28:29]
	s_barrier
	s_cbranch_scc0 .LBB0_133
	v_lshl_or_b32 v132, s12, 8, v158
	v_lshl_add_u32 v130, s2, 8, v156
	v_ashrrev_i32_e32 v133, 31, v132
	v_lshlrev_b64 v[148:149], 2, v[132:133]
	v_ashrrev_i32_e32 v131, 31, v130
	v_lshl_add_u64 v[150:151], s[4:5], 0, v[148:149]
	v_lshlrev_b64 v[152:153], 12, v[130:131]
	v_lshl_add_u64 v[132:133], v[150:151], 0, v[152:153]
	global_load_dwordx4 v[160:163], v[132:133], off
	global_load_dwordx4 v[164:167], v[132:133], off offset:64
	global_load_dwordx4 v[168:171], v[132:133], off offset:512
	global_load_dwordx4 v[172:175], v[132:133], off offset:576
	v_or_b32_e32 v132, 16, v130
	v_ashrrev_i32_e32 v133, 31, v132
	v_lshlrev_b64 v[196:197], 12, v[132:133]
	v_lshl_add_u64 v[132:133], v[150:151], 0, v[196:197]
	global_load_dwordx4 v[176:179], v[132:133], off
	global_load_dwordx4 v[180:183], v[132:133], off offset:64
	global_load_dwordx4 v[184:187], v[132:133], off offset:512
	global_load_dwordx4 v[188:191], v[132:133], off offset:576
	v_or_b32_e32 v132, 32, v130
	v_ashrrev_i32_e32 v133, 31, v132
	v_or_b32_e32 v130, 48, v130
	v_lshlrev_b64 v[224:225], 12, v[132:133]
	v_ashrrev_i32_e32 v131, 31, v130
	v_lshl_add_u64 v[132:133], v[150:151], 0, v[224:225]
	v_lshlrev_b64 v[154:155], 12, v[130:131]
	global_load_dwordx4 v[192:195], v[132:133], off
	global_load_dwordx4 v[208:211], v[132:133], off offset:64
	global_load_dwordx4 v[212:215], v[132:133], off offset:512
	global_load_dwordx4 v[216:219], v[132:133], off offset:576
	v_lshl_add_u64 v[130:131], v[150:151], 0, v[154:155]
	global_load_dwordx4 v[220:223], v[130:131], off
	global_load_dwordx4 v[138:141], v[130:131], off offset:64
	global_load_dwordx4 v[134:137], v[130:131], off offset:512
	s_nop 0
	global_load_dwordx4 v[130:133], v[130:131], off offset:576
	s_waitcnt vmcnt(0) lgkmcnt(0)
	v_pk_fma_f32 v[126:127], v[126:127], 0.5, v[160:161] op_sel_hi:[1,0,1]
	v_lshl_add_u64 v[160:161], s[14:15], 0, v[152:153]
	v_lshl_add_u64 v[160:161], v[160:161], 0, v[148:149]
	v_pk_fma_f32 v[116:117], v[116:117], 0.5, v[170:171] op_sel_hi:[1,0,1]
	v_pk_fma_f32 v[114:115], v[114:115], 0.5, v[168:169] op_sel_hi:[1,0,1]
	global_store_dwordx4 v[160:161], v[114:117], off offset:512
	v_pk_fma_f32 v[112:113], v[112:113], 0.5, v[174:175] op_sel_hi:[1,0,1]
	v_pk_fma_f32 v[100:101], v[100:101], 0.5, v[186:187] op_sel_hi:[1,0,1]
	v_lshl_add_u64 v[114:115], s[14:15], 0, v[196:197]
	v_lshl_add_u64 v[114:115], v[114:115], 0, v[148:149]
	v_pk_fma_f32 v[98:99], v[98:99], 0.5, v[184:185] op_sel_hi:[1,0,1]
	global_store_dwordx4 v[114:115], v[98:101], off offset:512
	v_pk_fma_f32 v[110:111], v[110:111], 0.5, v[172:173] op_sel_hi:[1,0,1]
	v_pk_fma_f32 v[96:97], v[96:97], 0.5, v[190:191] op_sel_hi:[1,0,1]
	v_lshl_add_u64 v[98:99], s[14:15], 0, v[224:225]
	v_lshl_add_u64 v[98:99], v[98:99], 0, v[148:149]
	v_pk_fma_f32 v[84:85], v[84:85], 0.5, v[214:215] op_sel_hi:[1,0,1]
	v_pk_fma_f32 v[82:83], v[82:83], 0.5, v[212:213] op_sel_hi:[1,0,1]
	v_pk_fma_f32 v[94:95], v[94:95], 0.5, v[188:189] op_sel_hi:[1,0,1]
	global_store_dwordx4 v[98:99], v[82:85], off offset:512
	v_pk_fma_f32 v[80:81], v[80:81], 0.5, v[218:219] op_sel_hi:[1,0,1]
	v_pk_fma_f32 v[78:79], v[78:79], 0.5, v[216:217] op_sel_hi:[1,0,1]
	v_lshl_add_u64 v[82:83], s[14:15], 0, v[154:155]
	v_pk_fma_f32 v[128:129], v[128:129], 0.5, v[162:163] op_sel_hi:[1,0,1]
	v_pk_fma_f32 v[124:125], v[124:125], 0.5, v[166:167] op_sel_hi:[1,0,1]
	v_pk_fma_f32 v[122:123], v[122:123], 0.5, v[164:165] op_sel_hi:[1,0,1]
	global_store_dwordx4 v[160:161], v[110:113], off offset:576
	v_pk_fma_f32 v[108:109], v[108:109], 0.5, v[182:183] op_sel_hi:[1,0,1]
	v_pk_fma_f32 v[106:107], v[106:107], 0.5, v[180:181] op_sel_hi:[1,0,1]
	v_pk_fma_f32 v[112:113], v[120:121], 0.5, v[178:179] op_sel_hi:[1,0,1]
	v_pk_fma_f32 v[110:111], v[118:119], 0.5, v[176:177] op_sel_hi:[1,0,1]
	global_store_dwordx4 v[114:115], v[94:97], off offset:576
	v_pk_fma_f32 v[92:93], v[92:93], 0.5, v[210:211] op_sel_hi:[1,0,1]
	v_pk_fma_f32 v[90:91], v[90:91], 0.5, v[208:209] op_sel_hi:[1,0,1]
	v_pk_fma_f32 v[96:97], v[104:105], 0.5, v[194:195] op_sel_hi:[1,0,1]
	v_pk_fma_f32 v[94:95], v[102:103], 0.5, v[192:193] op_sel_hi:[1,0,1]
	global_store_dwordx4 v[98:99], v[78:81], off offset:576
	v_lshl_add_u64 v[82:83], v[82:83], 0, v[148:149]
	v_pk_fma_f32 v[76:77], v[76:77], 0.5, v[140:141] op_sel_hi:[1,0,1]
	v_pk_fma_f32 v[80:81], v[88:89], 0.5, v[222:223] op_sel_hi:[1,0,1]
	v_pk_fma_f32 v[78:79], v[86:87], 0.5, v[220:221] op_sel_hi:[1,0,1]
	v_pk_fma_f32 v[74:75], v[74:75], 0.5, v[138:139] op_sel_hi:[1,0,1]
	v_pk_fma_f32 v[72:73], v[72:73], 0.5, v[136:137] op_sel_hi:[1,0,1]
	v_pk_fma_f32 v[70:71], v[70:71], 0.5, v[134:135] op_sel_hi:[1,0,1]
	v_pk_fma_f32 v[68:69], v[68:69], 0.5, v[132:133] op_sel_hi:[1,0,1]
	v_pk_fma_f32 v[66:67], v[66:67], 0.5, v[130:131] op_sel_hi:[1,0,1]
	global_store_dwordx4 v[160:161], v[126:129], off
	global_store_dwordx4 v[160:161], v[122:125], off offset:64
	global_store_dwordx4 v[114:115], v[110:113], off
	global_store_dwordx4 v[114:115], v[106:109], off offset:64
	global_store_dwordx4 v[98:99], v[94:97], off
	global_store_dwordx4 v[98:99], v[90:93], off offset:64
	global_store_dwordx4 v[82:83], v[78:81], off
	global_store_dwordx4 v[82:83], v[74:77], off offset:64
	global_store_dwordx4 v[82:83], v[70:73], off offset:512
	global_store_dwordx4 v[82:83], v[66:69], off offset:576
	s_mov_b64 s[22:23], 0x80000
	v_lshl_add_u64 v[130:131], v[152:153], 0, s[22:23]
	s_mov_b64 s[22:23], 0x90000
	v_lshl_add_u64 v[132:133], v[152:153], 0, s[22:23]
	s_mov_b64 s[22:23], 0xa0000
	v_lshl_add_u64 v[134:135], v[152:153], 0, s[22:23]
	s_mov_b64 s[22:23], 0xb0000
	v_lshl_add_u64 v[136:137], v[152:153], 0, s[22:23]
	v_lshl_add_u64 v[78:79], v[150:151], 0, v[130:131]
	v_lshl_add_u64 v[94:95], v[150:151], 0, v[132:133]
	v_lshl_add_u64 v[110:111], v[150:151], 0, v[134:135]
	v_lshl_add_u64 v[126:127], v[150:151], 0, v[136:137]
	global_load_dwordx4 v[66:69], v[78:79], off
	global_load_dwordx4 v[70:73], v[78:79], off offset:64
	global_load_dwordx4 v[74:77], v[78:79], off offset:512
	v_lshl_add_u64 v[130:131], s[14:15], 0, v[130:131]
	global_load_dwordx4 v[78:81], v[78:79], off offset:576
	s_nop 0
	global_load_dwordx4 v[82:85], v[94:95], off
	global_load_dwordx4 v[86:89], v[94:95], off offset:64
	global_load_dwordx4 v[90:93], v[94:95], off offset:512
	v_lshl_add_u64 v[132:133], s[14:15], 0, v[132:133]
	global_load_dwordx4 v[94:97], v[94:95], off offset:576
	s_nop 0
	global_load_dwordx4 v[98:101], v[110:111], off
	global_load_dwordx4 v[102:105], v[110:111], off offset:64
	global_load_dwordx4 v[106:109], v[110:111], off offset:512
	v_lshl_add_u64 v[134:135], s[14:15], 0, v[134:135]
	global_load_dwordx4 v[110:113], v[110:111], off offset:576
	s_nop 0
	global_load_dwordx4 v[114:117], v[126:127], off
	global_load_dwordx4 v[118:121], v[126:127], off offset:64
	global_load_dwordx4 v[122:125], v[126:127], off offset:512
	s_nop 0
	global_load_dwordx4 v[126:129], v[126:127], off offset:576
	v_lshl_add_u64 v[136:137], s[14:15], 0, v[136:137]
	v_lshl_add_u64 v[130:131], v[130:131], 0, v[148:149]
	v_lshl_add_u64 v[132:133], v[132:133], 0, v[148:149]
	v_lshl_add_u64 v[134:135], v[134:135], 0, v[148:149]
	v_lshl_add_u64 v[136:137], v[136:137], 0, v[148:149]
	s_waitcnt vmcnt(0) lgkmcnt(0)
	v_pk_fma_f32 v[64:65], v[64:65], 0.5, v[68:69] op_sel_hi:[1,0,1]
	v_pk_fma_f32 v[62:63], v[62:63], 0.5, v[66:67] op_sel_hi:[1,0,1]
	v_pk_fma_f32 v[60:61], v[60:61], 0.5, v[72:73] op_sel_hi:[1,0,1]
	v_pk_fma_f32 v[58:59], v[58:59], 0.5, v[70:71] op_sel_hi:[1,0,1]
	v_pk_fma_f32 v[44:45], v[44:45], 0.5, v[76:77] op_sel_hi:[1,0,1]
	v_pk_fma_f32 v[42:43], v[42:43], 0.5, v[74:75] op_sel_hi:[1,0,1]
	v_pk_fma_f32 v[36:37], v[36:37], 0.5, v[80:81] op_sel_hi:[1,0,1]
	v_pk_fma_f32 v[34:35], v[34:35], 0.5, v[78:79] op_sel_hi:[1,0,1]
	v_pk_fma_f32 v[56:57], v[56:57], 0.5, v[84:85] op_sel_hi:[1,0,1]
	v_pk_fma_f32 v[54:55], v[54:55], 0.5, v[82:83] op_sel_hi:[1,0,1]
	v_pk_fma_f32 v[52:53], v[52:53], 0.5, v[88:89] op_sel_hi:[1,0,1]
	v_pk_fma_f32 v[50:51], v[50:51], 0.5, v[86:87] op_sel_hi:[1,0,1]
	v_pk_fma_f32 v[28:29], v[28:29], 0.5, v[92:93] op_sel_hi:[1,0,1]
	v_pk_fma_f32 v[26:27], v[26:27], 0.5, v[90:91] op_sel_hi:[1,0,1]
	v_pk_fma_f32 v[24:25], v[24:25], 0.5, v[96:97] op_sel_hi:[1,0,1]
	v_pk_fma_f32 v[22:23], v[22:23], 0.5, v[94:95] op_sel_hi:[1,0,1]
	v_pk_fma_f32 v[48:49], v[48:49], 0.5, v[100:101] op_sel_hi:[1,0,1]
	v_pk_fma_f32 v[46:47], v[46:47], 0.5, v[98:99] op_sel_hi:[1,0,1]
	v_pk_fma_f32 v[40:41], v[40:41], 0.5, v[104:105] op_sel_hi:[1,0,1]
	v_pk_fma_f32 v[38:39], v[38:39], 0.5, v[102:103] op_sel_hi:[1,0,1]
	v_pk_fma_f32 v[14:15], v[14:15], 0.5, v[108:109] op_sel_hi:[1,0,1]
	v_pk_fma_f32 v[12:13], v[12:13], 0.5, v[106:107] op_sel_hi:[1,0,1]
	v_pk_fma_f32 v[10:11], v[10:11], 0.5, v[112:113] op_sel_hi:[1,0,1]
	v_pk_fma_f32 v[8:9], v[8:9], 0.5, v[110:111] op_sel_hi:[1,0,1]
	v_pk_fma_f32 v[32:33], v[32:33], 0.5, v[116:117] op_sel_hi:[1,0,1]
	v_pk_fma_f32 v[30:31], v[30:31], 0.5, v[114:115] op_sel_hi:[1,0,1]
	v_pk_fma_f32 v[20:21], v[20:21], 0.5, v[120:121] op_sel_hi:[1,0,1]
	v_pk_fma_f32 v[18:19], v[18:19], 0.5, v[118:119] op_sel_hi:[1,0,1]
	v_pk_fma_f32 v[6:7], v[6:7], 0.5, v[124:125] op_sel_hi:[1,0,1]
	v_pk_fma_f32 v[4:5], v[4:5], 0.5, v[122:123] op_sel_hi:[1,0,1]
	v_pk_fma_f32 v[2:3], v[2:3], 0.5, v[128:129] op_sel_hi:[1,0,1]
	v_pk_fma_f32 v[0:1], v[0:1], 0.5, v[126:127] op_sel_hi:[1,0,1]
	global_store_dwordx4 v[130:131], v[62:65], off
	global_store_dwordx4 v[130:131], v[58:61], off offset:64
	global_store_dwordx4 v[130:131], v[42:45], off offset:512
	global_store_dwordx4 v[130:131], v[34:37], off offset:576
	global_store_dwordx4 v[132:133], v[54:57], off
	global_store_dwordx4 v[132:133], v[50:53], off offset:64
	global_store_dwordx4 v[132:133], v[26:29], off offset:512
	global_store_dwordx4 v[132:133], v[22:25], off offset:576
	global_store_dwordx4 v[134:135], v[46:49], off
	global_store_dwordx4 v[134:135], v[38:41], off offset:64
	global_store_dwordx4 v[134:135], v[12:15], off offset:512
	global_store_dwordx4 v[134:135], v[8:11], off offset:576
	global_store_dwordx4 v[136:137], v[30:33], off
	global_store_dwordx4 v[136:137], v[18:21], off offset:64
	global_store_dwordx4 v[136:137], v[4:7], off offset:512
	global_store_dwordx4 v[136:137], v[0:3], off offset:576
	s_and_b64 vcc, exec, s[38:39]
	s_mov_b32 s12, s82
	s_mov_b32 s2, s83
	s_mov_b64 s[28:29], s[18:19]
	s_mov_b64 s[22:23], s[16:17]
	s_mov_b32 s86, 0x38c0000
	s_cbranch_vccz .LBB0_122
	s_waitcnt vmcnt(0)
	s_cmpk_gt_u32 s48, 0xff
	s_cbranch_scc1 .LBB0_137
	s_barrier

.LBB0_147:
	s_add_u32 s18, s16, 0xfffc0080
	s_addc_u32 s19, s17, -1
	s_add_i32 s83, 0, 0x10000
	v_add_u32_e32 v140, s83, v143
	ds_read_b128 v[146:149], v140
	ds_read_b128 v[150:153], v140 offset:1024
	ds_read_b128 v[154:157], v140 offset:2048
	ds_read_b128 v[158:161], v140 offset:3072
	s_cmp_eq_u32 s82, 12
	s_cselect_b32 s23, s12, s19
	s_cselect_b32 s22, s29, s18
	s_cselect_b32 s19, s9, s79
	s_cselect_b32 s18, s34, s61
	v_lshl_add_u64 v[140:141], s[16:17], 0, v[138:139]
	s_add_i32 m0, s15, 0xc000
	ds_read_b128 v[162:165], v145
	ds_read_b128 v[166:169], v145 offset:1024
	ds_read_b128 v[170:173], v145 offset:2048
	ds_read_b128 v[174:177], v145 offset:3072
	ds_read_b128 v[178:181], v145 offset:4096
	ds_read_b128 v[182:185], v145 offset:5120
	ds_read_b128 v[186:189], v145 offset:6144
	ds_read_b128 v[190:193], v145 offset:7168
	global_load_lds_dwordx4 v[140:141], off
	v_lshl_add_u64 v[140:141], s[16:17], 0, v[136:137]
	s_add_i32 m0, s15, 0xe000
	s_nop 0
	global_load_lds_dwordx4 v[140:141], off
	s_waitcnt lgkmcnt(8)
	s_waitcnt vmcnt(10)
	s_barrier
	s_waitcnt lgkmcnt(0)
	s_waitcnt lgkmcnt(0)
	v_mfma_f32_16x16x32_bf16 v[126:129], v[146:149], v[162:165], v[126:129]
	v_mfma_f32_16x16x32_bf16 v[118:121], v[154:157], v[162:165], v[118:121]
	v_mfma_f32_16x16x32_bf16 v[110:113], v[146:149], v[170:173], v[110:113]
	v_mfma_f32_16x16x32_bf16 v[102:105], v[154:157], v[170:173], v[102:105]
	v_mfma_f32_16x16x32_bf16 v[94:97], v[146:149], v[178:181], v[94:97]
	v_mfma_f32_16x16x32_bf16 v[86:89], v[154:157], v[178:181], v[86:89]
	v_mfma_f32_16x16x32_bf16 v[78:81], v[146:149], v[186:189], v[78:81]
	v_mfma_f32_16x16x32_bf16 v[70:73], v[154:157], v[186:189], v[70:73]
	v_mfma_f32_16x16x32_bf16 v[126:129], v[150:153], v[166:169], v[126:129]
	v_mfma_f32_16x16x32_bf16 v[118:121], v[158:161], v[166:169], v[118:121]
	v_mfma_f32_16x16x32_bf16 v[110:113], v[150:153], v[174:177], v[110:113]
	v_mfma_f32_16x16x32_bf16 v[102:105], v[158:161], v[174:177], v[102:105]
	v_mfma_f32_16x16x32_bf16 v[94:97], v[150:153], v[182:185], v[94:97]
	v_mfma_f32_16x16x32_bf16 v[86:89], v[158:161], v[182:185], v[86:89]
	v_mfma_f32_16x16x32_bf16 v[78:81], v[150:153], v[190:193], v[78:81]
	v_mfma_f32_16x16x32_bf16 v[70:73], v[158:161], v[190:193], v[70:73]
	s_barrier
	s_add_i32 s86, 0, 0x14000
	v_add_u32_e32 v140, s86, v143
	s_add_i32 s83, s83, s51
	ds_read_b128 v[194:197], v140
	ds_read_b128 v[208:211], v140 offset:1024
	ds_read_b128 v[212:215], v140 offset:2048
	ds_read_b128 v[216:219], v140 offset:3072
	v_lshl_add_u64 v[140:141], s[18:19], 0, v[16:17]
	s_mov_b32 m0, s83
	v_lshl_add_u64 v[220:221], s[18:19], 0, v[130:131]
	global_load_lds_dwordx4 v[140:141], off
	s_add_i32 m0, s83, 0x2000
	s_nop 0
	global_load_lds_dwordx4 v[220:221], off
	s_waitcnt vmcnt(10)
	s_barrier
	s_waitcnt lgkmcnt(0)
	s_waitcnt lgkmcnt(0)
	v_mfma_f32_16x16x32_bf16 v[122:125], v[194:197], v[162:165], v[122:125]
	v_mfma_f32_16x16x32_bf16 v[114:117], v[212:215], v[162:165], v[114:117]
	v_mfma_f32_16x16x32_bf16 v[106:109], v[194:197], v[170:173], v[106:109]
	v_mfma_f32_16x16x32_bf16 v[98:101], v[212:215], v[170:173], v[98:101]
	v_mfma_f32_16x16x32_bf16 v[90:93], v[194:197], v[178:181], v[90:93]
	v_mfma_f32_16x16x32_bf16 v[82:85], v[212:215], v[178:181], v[82:85]
	v_mfma_f32_16x16x32_bf16 v[74:77], v[194:197], v[186:189], v[74:77]
	v_mfma_f32_16x16x32_bf16 v[66:69], v[212:215], v[186:189], v[66:69]
	v_mfma_f32_16x16x32_bf16 v[122:125], v[208:211], v[166:169], v[122:125]
	v_mfma_f32_16x16x32_bf16 v[114:117], v[216:219], v[166:169], v[114:117]
	v_mfma_f32_16x16x32_bf16 v[106:109], v[208:211], v[174:177], v[106:109]
	v_mfma_f32_16x16x32_bf16 v[98:101], v[216:219], v[174:177], v[98:101]
	v_mfma_f32_16x16x32_bf16 v[90:93], v[208:211], v[182:185], v[90:93]
	v_mfma_f32_16x16x32_bf16 v[82:85], v[216:219], v[182:185], v[82:85]
	v_mfma_f32_16x16x32_bf16 v[74:77], v[208:211], v[190:193], v[74:77]
	v_mfma_f32_16x16x32_bf16 v[66:69], v[216:219], v[190:193], v[66:69]
	s_mov_b32 m0, s15
	v_lshl_add_u64 v[222:223], s[22:23], 0, v[134:135]
	s_barrier
	ds_read_b128 v[162:165], v145 offset:16384
	ds_read_b128 v[166:169], v145 offset:17408
	ds_read_b128 v[170:173], v145 offset:18432
	ds_read_b128 v[174:177], v145 offset:19456
	ds_read_b128 v[178:181], v145 offset:20480
	ds_read_b128 v[182:185], v145 offset:21504
	ds_read_b128 v[186:189], v145 offset:22528
	ds_read_b128 v[190:193], v145 offset:23552
	global_load_lds_dwordx4 v[222:223], off
	v_lshl_add_u64 v[224:225], s[22:23], 0, v[132:133]
	s_mov_b32 m0, s54
	s_nop 0
	global_load_lds_dwordx4 v[224:225], off
	s_barrier
	s_waitcnt lgkmcnt(0)
	s_waitcnt lgkmcnt(0)
	v_mfma_f32_16x16x32_bf16 v[62:65], v[146:149], v[162:165], v[62:65]
	v_mfma_f32_16x16x32_bf16 v[54:57], v[154:157], v[162:165], v[54:57]
	v_mfma_f32_16x16x32_bf16 v[46:49], v[146:149], v[170:173], v[46:49]
	v_mfma_f32_16x16x32_bf16 v[38:41], v[154:157], v[170:173], v[38:41]
	v_mfma_f32_16x16x32_bf16 v[30:33], v[146:149], v[178:181], v[30:33]
	v_mfma_f32_16x16x32_bf16 v[22:25], v[154:157], v[178:181], v[22:25]
	v_mfma_f32_16x16x32_bf16 v[12:15], v[146:149], v[186:189], v[12:15]
	v_mfma_f32_16x16x32_bf16 v[4:7], v[154:157], v[186:189], v[4:7]
	v_mfma_f32_16x16x32_bf16 v[62:65], v[150:153], v[166:169], v[62:65]
	v_mfma_f32_16x16x32_bf16 v[54:57], v[158:161], v[166:169], v[54:57]
	v_mfma_f32_16x16x32_bf16 v[46:49], v[150:153], v[174:177], v[46:49]
	v_mfma_f32_16x16x32_bf16 v[38:41], v[158:161], v[174:177], v[38:41]
	v_mfma_f32_16x16x32_bf16 v[30:33], v[150:153], v[182:185], v[30:33]
	v_mfma_f32_16x16x32_bf16 v[22:25], v[158:161], v[182:185], v[22:25]
	v_mfma_f32_16x16x32_bf16 v[12:15], v[150:153], v[190:193], v[12:15]
	v_mfma_f32_16x16x32_bf16 v[4:7], v[158:161], v[190:193], v[4:7]
	s_barrier
	s_add_u32 s84, s18, 0x40000
	s_addc_u32 s85, s19, 0
	s_add_i32 s83, s86, s51
	v_lshl_add_u64 v[146:147], s[84:85], 0, v[16:17]
	s_mov_b32 m0, s83
	s_nop 0
	global_load_lds_dwordx4 v[146:147], off
	v_lshl_add_u64 v[146:147], s[84:85], 0, v[130:131]
	s_add_i32 m0, s83, 0x2000
	s_nop 0
	global_load_lds_dwordx4 v[146:147], off
	s_waitcnt vmcnt(10)
	s_barrier
	v_mfma_f32_16x16x32_bf16 v[58:61], v[194:197], v[162:165], v[58:61]
	v_mfma_f32_16x16x32_bf16 v[50:53], v[212:215], v[162:165], v[50:53]
	v_mfma_f32_16x16x32_bf16 v[42:45], v[194:197], v[170:173], v[42:45]
	v_mfma_f32_16x16x32_bf16 v[34:37], v[212:215], v[170:173], v[34:37]
	v_mfma_f32_16x16x32_bf16 v[26:29], v[194:197], v[178:181], v[26:29]
	v_mfma_f32_16x16x32_bf16 v[18:21], v[212:215], v[178:181], v[18:21]
	v_mfma_f32_16x16x32_bf16 v[8:11], v[194:197], v[186:189], v[8:11]
	v_mfma_f32_16x16x32_bf16 v[0:3], v[212:215], v[186:189], v[0:3]
	v_mfma_f32_16x16x32_bf16 v[58:61], v[208:211], v[166:169], v[58:61]
	v_mfma_f32_16x16x32_bf16 v[50:53], v[216:219], v[166:169], v[50:53]
	v_mfma_f32_16x16x32_bf16 v[42:45], v[208:211], v[174:177], v[42:45]
	v_mfma_f32_16x16x32_bf16 v[34:37], v[216:219], v[174:177], v[34:37]
	v_mfma_f32_16x16x32_bf16 v[26:29], v[208:211], v[182:185], v[26:29]
	v_mfma_f32_16x16x32_bf16 v[18:21], v[216:219], v[182:185], v[18:21]
	v_mfma_f32_16x16x32_bf16 v[8:11], v[208:211], v[190:193], v[8:11]
	v_mfma_f32_16x16x32_bf16 v[0:3], v[216:219], v[190:193], v[0:3]
	s_add_i32 s83, 0, 0x18000
	v_add_u32_e32 v158, s83, v143
	s_barrier
	ds_read_b128 v[146:149], v158
	ds_read_b128 v[150:153], v158 offset:1024
	ds_read_b128 v[154:157], v158 offset:2048
	ds_read_b128 v[158:161], v158 offset:3072
	s_add_u32 s22, s22, 0x40000
	s_addc_u32 s23, s23, 0
	s_mov_b32 m0, s55
	v_lshl_add_u64 v[194:195], s[22:23], 0, v[134:135]
	ds_read_b128 v[162:165], v145 offset:32768
	ds_read_b128 v[166:169], v145 offset:33792
	ds_read_b128 v[170:173], v145 offset:34816
	ds_read_b128 v[174:177], v145 offset:35840
	ds_read_b128 v[178:181], v145 offset:36864
	ds_read_b128 v[182:185], v145 offset:37888
	ds_read_b128 v[186:189], v145 offset:38912
	ds_read_b128 v[190:193], v145 offset:39936
	global_load_lds_dwordx4 v[194:195], off
	v_lshl_add_u64 v[194:195], s[22:23], 0, v[132:133]
	s_mov_b32 m0, s56
	s_nop 0
	global_load_lds_dwordx4 v[194:195], off
	s_waitcnt lgkmcnt(8)
	s_waitcnt vmcnt(10)
	s_barrier
	s_waitcnt lgkmcnt(0)
	s_waitcnt lgkmcnt(0)
	v_mfma_f32_16x16x32_bf16 v[126:129], v[146:149], v[162:165], v[126:129]
	v_mfma_f32_16x16x32_bf16 v[118:121], v[154:157], v[162:165], v[118:121]
	v_mfma_f32_16x16x32_bf16 v[110:113], v[146:149], v[170:173], v[110:113]
	v_mfma_f32_16x16x32_bf16 v[102:105], v[154:157], v[170:173], v[102:105]
	v_mfma_f32_16x16x32_bf16 v[94:97], v[146:149], v[178:181], v[94:97]
	v_mfma_f32_16x16x32_bf16 v[86:89], v[154:157], v[178:181], v[86:89]
	v_mfma_f32_16x16x32_bf16 v[78:81], v[146:149], v[186:189], v[78:81]
	v_mfma_f32_16x16x32_bf16 v[70:73], v[154:157], v[186:189], v[70:73]
	v_mfma_f32_16x16x32_bf16 v[126:129], v[150:153], v[166:169], v[126:129]
	v_mfma_f32_16x16x32_bf16 v[118:121], v[158:161], v[166:169], v[118:121]
	v_mfma_f32_16x16x32_bf16 v[110:113], v[150:153], v[174:177], v[110:113]
	v_mfma_f32_16x16x32_bf16 v[102:105], v[158:161], v[174:177], v[102:105]
	v_mfma_f32_16x16x32_bf16 v[94:97], v[150:153], v[182:185], v[94:97]
	v_mfma_f32_16x16x32_bf16 v[86:89], v[158:161], v[182:185], v[86:89]
	v_mfma_f32_16x16x32_bf16 v[78:81], v[150:153], v[190:193], v[78:81]
	v_mfma_f32_16x16x32_bf16 v[70:73], v[158:161], v[190:193], v[70:73]
	s_barrier
	s_add_i32 s22, 0, 0x1c000
	s_add_i32 s23, s83, s51
	v_add_u32_e32 v216, s22, v143
	v_lshl_add_u64 v[140:141], v[140:141], 0, s[10:11]
	s_mov_b32 m0, s23
	ds_read_b128 v[194:197], v216
	ds_read_b128 v[208:211], v216 offset:1024
	ds_read_b128 v[212:215], v216 offset:2048
	ds_read_b128 v[216:219], v216 offset:3072
	global_load_lds_dwordx4 v[140:141], off
	v_lshl_add_u64 v[140:141], v[220:221], 0, s[10:11]
	s_add_i32 m0, s23, 0x2000
	s_nop 0
	global_load_lds_dwordx4 v[140:141], off
	s_waitcnt vmcnt(10)
	s_barrier
	s_waitcnt lgkmcnt(0)
	s_waitcnt lgkmcnt(0)
	v_mfma_f32_16x16x32_bf16 v[122:125], v[194:197], v[162:165], v[122:125]
	v_mfma_f32_16x16x32_bf16 v[114:117], v[212:215], v[162:165], v[114:117]
	v_mfma_f32_16x16x32_bf16 v[106:109], v[194:197], v[170:173], v[106:109]
	v_mfma_f32_16x16x32_bf16 v[98:101], v[212:215], v[170:173], v[98:101]
	v_mfma_f32_16x16x32_bf16 v[90:93], v[194:197], v[178:181], v[90:93]
	v_mfma_f32_16x16x32_bf16 v[82:85], v[212:215], v[178:181], v[82:85]
	v_mfma_f32_16x16x32_bf16 v[74:77], v[194:197], v[186:189], v[74:77]
	v_mfma_f32_16x16x32_bf16 v[66:69], v[212:215], v[186:189], v[66:69]
	v_mfma_f32_16x16x32_bf16 v[122:125], v[208:211], v[166:169], v[122:125]
	v_mfma_f32_16x16x32_bf16 v[114:117], v[216:219], v[166:169], v[114:117]
	v_mfma_f32_16x16x32_bf16 v[106:109], v[208:211], v[174:177], v[106:109]
	v_mfma_f32_16x16x32_bf16 v[98:101], v[216:219], v[174:177], v[98:101]
	v_mfma_f32_16x16x32_bf16 v[90:93], v[208:211], v[182:185], v[90:93]
	v_mfma_f32_16x16x32_bf16 v[82:85], v[216:219], v[182:185], v[82:85]
	v_mfma_f32_16x16x32_bf16 v[74:77], v[208:211], v[190:193], v[74:77]
	v_mfma_f32_16x16x32_bf16 v[66:69], v[216:219], v[190:193], v[66:69]
	s_mov_b32 m0, s57
	v_lshl_add_u64 v[140:141], v[222:223], 0, s[10:11]
	s_barrier
	ds_read_b128 v[162:165], v145 offset:49152
	ds_read_b128 v[166:169], v145 offset:50176
	ds_read_b128 v[170:173], v145 offset:51200
	ds_read_b128 v[174:177], v145 offset:52224
	ds_read_b128 v[178:181], v145 offset:53248
	ds_read_b128 v[182:185], v145 offset:54272
	ds_read_b128 v[186:189], v145 offset:55296
	ds_read_b128 v[190:193], v145 offset:56320
	global_load_lds_dwordx4 v[140:141], off
	v_lshl_add_u64 v[140:141], v[224:225], 0, s[10:11]
	s_mov_b32 m0, s58
	s_nop 0
	global_load_lds_dwordx4 v[140:141], off
	s_barrier
	s_waitcnt lgkmcnt(0)
	s_waitcnt lgkmcnt(0)
	v_mfma_f32_16x16x32_bf16 v[62:65], v[146:149], v[162:165], v[62:65]
	v_mfma_f32_16x16x32_bf16 v[54:57], v[154:157], v[162:165], v[54:57]
	v_mfma_f32_16x16x32_bf16 v[46:49], v[146:149], v[170:173], v[46:49]
	v_mfma_f32_16x16x32_bf16 v[38:41], v[154:157], v[170:173], v[38:41]
	v_mfma_f32_16x16x32_bf16 v[30:33], v[146:149], v[178:181], v[30:33]
	v_mfma_f32_16x16x32_bf16 v[22:25], v[154:157], v[178:181], v[22:25]
	v_mfma_f32_16x16x32_bf16 v[12:15], v[146:149], v[186:189], v[12:15]
	v_mfma_f32_16x16x32_bf16 v[4:7], v[154:157], v[186:189], v[4:7]
	v_mfma_f32_16x16x32_bf16 v[62:65], v[150:153], v[166:169], v[62:65]
	v_mfma_f32_16x16x32_bf16 v[54:57], v[158:161], v[166:169], v[54:57]
	v_mfma_f32_16x16x32_bf16 v[46:49], v[150:153], v[174:177], v[46:49]
	v_mfma_f32_16x16x32_bf16 v[38:41], v[158:161], v[174:177], v[38:41]
	v_mfma_f32_16x16x32_bf16 v[30:33], v[150:153], v[182:185], v[30:33]
	v_mfma_f32_16x16x32_bf16 v[22:25], v[158:161], v[182:185], v[22:25]
	v_mfma_f32_16x16x32_bf16 v[12:15], v[150:153], v[190:193], v[12:15]
	v_mfma_f32_16x16x32_bf16 v[4:7], v[158:161], v[190:193], v[4:7]
	s_barrier
	s_add_u32 s18, s18, 0x40080
	s_addc_u32 s19, s19, 0
	s_add_i32 s22, s22, s51
	v_lshl_add_u64 v[140:141], s[18:19], 0, v[16:17]
	s_mov_b32 m0, s22
	s_nop 0
	global_load_lds_dwordx4 v[140:141], off
	v_lshl_add_u64 v[140:141], s[18:19], 0, v[130:131]
	s_add_i32 m0, s22, 0x2000
	s_nop 0
	global_load_lds_dwordx4 v[140:141], off
	s_waitcnt vmcnt(10)
	s_barrier
	v_mfma_f32_16x16x32_bf16 v[58:61], v[194:197], v[162:165], v[58:61]
	v_mfma_f32_16x16x32_bf16 v[50:53], v[212:215], v[162:165], v[50:53]
	v_mfma_f32_16x16x32_bf16 v[42:45], v[194:197], v[170:173], v[42:45]
	v_mfma_f32_16x16x32_bf16 v[34:37], v[212:215], v[170:173], v[34:37]
	v_mfma_f32_16x16x32_bf16 v[26:29], v[194:197], v[178:181], v[26:29]
	v_mfma_f32_16x16x32_bf16 v[18:21], v[212:215], v[178:181], v[18:21]
	v_mfma_f32_16x16x32_bf16 v[8:11], v[194:197], v[186:189], v[8:11]
	v_mfma_f32_16x16x32_bf16 v[0:3], v[212:215], v[186:189], v[0:3]
	v_mfma_f32_16x16x32_bf16 v[58:61], v[208:211], v[166:169], v[58:61]
	v_mfma_f32_16x16x32_bf16 v[50:53], v[216:219], v[166:169], v[50:53]
	v_mfma_f32_16x16x32_bf16 v[42:45], v[208:211], v[174:177], v[42:45]
	v_mfma_f32_16x16x32_bf16 v[34:37], v[216:219], v[174:177], v[34:37]
	v_mfma_f32_16x16x32_bf16 v[26:29], v[208:211], v[182:185], v[26:29]
	v_mfma_f32_16x16x32_bf16 v[18:21], v[216:219], v[182:185], v[18:21]
	v_mfma_f32_16x16x32_bf16 v[8:11], v[208:211], v[190:193], v[8:11]
	v_mfma_f32_16x16x32_bf16 v[0:3], v[216:219], v[190:193], v[0:3]
	s_add_i32 s82, s82, 2
	s_add_u32 s61, s61, 0x100
	s_addc_u32 s79, s79, 0
	s_add_u32 s16, s16, 0x100
	s_addc_u32 s17, s17, 0
	s_cmp_gt_u32 s82, 13
	s_barrier
	s_cbranch_scc0 .LBB0_147
	v_mul_f32_e32 v208, 0xbfb8aa3b, v126
	v_mul_f32_e32 v209, 0xbfb8aa3b, v127
	v_mul_f32_e32 v210, 0xbfb8aa3b, v128
	v_mul_f32_e32 v211, 0xbfb8aa3b, v129
	v_mul_f32_e32 v212, 0xbfb8aa3b, v118
	v_mul_f32_e32 v213, 0xbfb8aa3b, v119
	v_mul_f32_e32 v214, 0xbfb8aa3b, v120
	v_mul_f32_e32 v215, 0xbfb8aa3b, v121
	v_exp_f32_e32 v208, v208
	v_exp_f32_e32 v209, v209
	v_exp_f32_e32 v210, v210
	v_exp_f32_e32 v211, v211
	v_exp_f32_e32 v212, v212
	v_exp_f32_e32 v213, v213
	v_exp_f32_e32 v214, v214
	v_exp_f32_e32 v215, v215
	v_add_f32_e32 v208, 1.0, v208
	v_add_f32_e32 v209, 1.0, v209
	v_add_f32_e32 v210, 1.0, v210
	v_add_f32_e32 v211, 1.0, v211
	v_add_f32_e32 v212, 1.0, v212
	v_add_f32_e32 v213, 1.0, v213
	v_add_f32_e32 v214, 1.0, v214
	v_add_f32_e32 v215, 1.0, v215
	v_rcp_f32_e32 v208, v208
	v_rcp_f32_e32 v209, v209
	v_rcp_f32_e32 v210, v210
	v_rcp_f32_e32 v211, v211
	v_rcp_f32_e32 v212, v212
	v_rcp_f32_e32 v213, v213
	v_rcp_f32_e32 v214, v214
	v_rcp_f32_e32 v215, v215
	v_mul_f32_e32 v216, v126, v208
	v_mul_f32_e32 v217, v127, v209
	v_mul_f32_e32 v218, v128, v210
	v_mul_f32_e32 v219, v129, v211
	v_mul_f32_e32 v220, v118, v212
	v_mul_f32_e32 v221, v119, v213
	v_mul_f32_e32 v222, v120, v214
	v_mul_f32_e32 v223, v121, v215
	v_mul_f32_e32 v216, v216, v122
	v_mul_f32_e32 v217, v217, v123
	v_mul_f32_e32 v218, v218, v124
	v_mul_f32_e32 v219, v219, v125
	v_mul_f32_e32 v220, v220, v114
	v_mul_f32_e32 v221, v221, v115
	v_mul_f32_e32 v222, v222, v116
	v_mul_f32_e32 v223, v223, v117
	v_lshl_or_b32 v148, s2, 7, v144
	v_lshl_add_u32 v146, s14, 8, v142
	v_ashrrev_i32_e32 v149, 31, v148
	v_mov_b64_e32 v[140:141], s[94:95]
	v_mad_i64_i32 v[150:151], s[16:17], v146, s65, v[140:141]
	v_lshlrev_b64 v[114:115], 1, v[148:149]
	v_lshl_add_u64 v[120:121], v[150:151], 0, v[114:115]
	v_cvt_pk_bf16_f32 v116, v216, v217
	v_cvt_pk_bf16_f32 v117, v218, v219
	v_cvt_pk_bf16_f32 v118, v220, v221
	v_cvt_pk_bf16_f32 v119, v222, v223
	global_store_dwordx4 v[120:121], v[116:119], off
	v_mul_f32_e32 v208, 0xbfb8aa3b, v110
	v_mul_f32_e32 v209, 0xbfb8aa3b, v111
	v_mul_f32_e32 v210, 0xbfb8aa3b, v112
	v_mul_f32_e32 v211, 0xbfb8aa3b, v113
	v_mul_f32_e32 v212, 0xbfb8aa3b, v102
	v_mul_f32_e32 v213, 0xbfb8aa3b, v103
	v_mul_f32_e32 v214, 0xbfb8aa3b, v104
	v_mul_f32_e32 v215, 0xbfb8aa3b, v105
	v_exp_f32_e32 v208, v208
	v_exp_f32_e32 v209, v209
	v_exp_f32_e32 v210, v210
	v_exp_f32_e32 v211, v211
	v_exp_f32_e32 v212, v212
	v_exp_f32_e32 v213, v213
	v_exp_f32_e32 v214, v214
	v_exp_f32_e32 v215, v215
	v_add_f32_e32 v208, 1.0, v208
	v_add_f32_e32 v209, 1.0, v209
	v_add_f32_e32 v210, 1.0, v210
	v_add_f32_e32 v211, 1.0, v211
	v_add_f32_e32 v212, 1.0, v212
	v_add_f32_e32 v213, 1.0, v213
	v_add_f32_e32 v214, 1.0, v214
	v_add_f32_e32 v215, 1.0, v215
	v_rcp_f32_e32 v208, v208
	v_rcp_f32_e32 v209, v209
	v_rcp_f32_e32 v210, v210
	v_rcp_f32_e32 v211, v211
	v_rcp_f32_e32 v212, v212
	v_rcp_f32_e32 v213, v213
	v_rcp_f32_e32 v214, v214
	v_rcp_f32_e32 v215, v215
	v_mul_f32_e32 v216, v110, v208
	v_mul_f32_e32 v217, v111, v209
	v_mul_f32_e32 v218, v112, v210
	v_mul_f32_e32 v219, v113, v211
	v_mul_f32_e32 v220, v102, v212
	v_mul_f32_e32 v221, v103, v213
	v_mul_f32_e32 v222, v104, v214
	v_mul_f32_e32 v223, v105, v215
	v_mul_f32_e32 v216, v216, v106
	v_mul_f32_e32 v217, v217, v107
	v_mul_f32_e32 v218, v218, v108
	v_mul_f32_e32 v219, v219, v109
	v_mul_f32_e32 v220, v220, v98
	v_mul_f32_e32 v221, v221, v99
	v_mul_f32_e32 v222, v222, v100
	v_mul_f32_e32 v223, v223, v101
	v_or_b32_e32 v116, 16, v146
	v_mad_i64_i32 v[116:117], s[16:17], v116, s65, v[140:141]
	v_lshl_add_u64 v[102:103], v[116:117], 0, v[114:115]
	v_cvt_pk_bf16_f32 v98, v216, v217
	v_cvt_pk_bf16_f32 v99, v218, v219
	v_cvt_pk_bf16_f32 v100, v220, v221
	v_cvt_pk_bf16_f32 v101, v222, v223
	global_store_dwordx4 v[102:103], v[98:101], off
	v_mul_f32_e32 v208, 0xbfb8aa3b, v94
	v_mul_f32_e32 v209, 0xbfb8aa3b, v95
	v_mul_f32_e32 v210, 0xbfb8aa3b, v96
	v_mul_f32_e32 v211, 0xbfb8aa3b, v97
	v_mul_f32_e32 v212, 0xbfb8aa3b, v86
	v_mul_f32_e32 v213, 0xbfb8aa3b, v87
	v_mul_f32_e32 v214, 0xbfb8aa3b, v88
	v_mul_f32_e32 v215, 0xbfb8aa3b, v89
	v_exp_f32_e32 v208, v208
	v_exp_f32_e32 v209, v209
	v_exp_f32_e32 v210, v210
	v_exp_f32_e32 v211, v211
	v_exp_f32_e32 v212, v212
	v_exp_f32_e32 v213, v213
	v_exp_f32_e32 v214, v214
	v_exp_f32_e32 v215, v215
	v_add_f32_e32 v208, 1.0, v208
	v_add_f32_e32 v209, 1.0, v209
	v_add_f32_e32 v210, 1.0, v210
	v_add_f32_e32 v211, 1.0, v211
	v_add_f32_e32 v212, 1.0, v212
	v_add_f32_e32 v213, 1.0, v213
	v_add_f32_e32 v214, 1.0, v214
	v_add_f32_e32 v215, 1.0, v215
	v_rcp_f32_e32 v208, v208
	v_rcp_f32_e32 v209, v209
	v_rcp_f32_e32 v210, v210
	v_rcp_f32_e32 v211, v211
	v_rcp_f32_e32 v212, v212
	v_rcp_f32_e32 v213, v213
	v_rcp_f32_e32 v214, v214
	v_rcp_f32_e32 v215, v215
	v_mul_f32_e32 v216, v94, v208
	v_mul_f32_e32 v217, v95, v209
	v_mul_f32_e32 v218, v96, v210
	v_mul_f32_e32 v219, v97, v211
	v_mul_f32_e32 v220, v86, v212
	v_mul_f32_e32 v221, v87, v213
	v_mul_f32_e32 v222, v88, v214
	v_mul_f32_e32 v223, v89, v215
	v_mul_f32_e32 v216, v216, v90
	v_mul_f32_e32 v217, v217, v91
	v_mul_f32_e32 v218, v218, v92
	v_mul_f32_e32 v219, v219, v93
	v_mul_f32_e32 v220, v220, v82
	v_mul_f32_e32 v221, v221, v83
	v_mul_f32_e32 v222, v222, v84
	v_mul_f32_e32 v223, v223, v85
	v_or_b32_e32 v98, 32, v146
	v_mad_i64_i32 v[98:99], s[16:17], v98, s65, v[140:141]
	v_lshl_add_u64 v[86:87], v[98:99], 0, v[114:115]
	v_cvt_pk_bf16_f32 v82, v216, v217
	v_cvt_pk_bf16_f32 v83, v218, v219
	v_cvt_pk_bf16_f32 v84, v220, v221
	v_cvt_pk_bf16_f32 v85, v222, v223
	global_store_dwordx4 v[86:87], v[82:85], off
	v_mul_f32_e32 v208, 0xbfb8aa3b, v78
	v_mul_f32_e32 v209, 0xbfb8aa3b, v79
	v_mul_f32_e32 v210, 0xbfb8aa3b, v80
	v_mul_f32_e32 v211, 0xbfb8aa3b, v81
	v_mul_f32_e32 v212, 0xbfb8aa3b, v70
	v_mul_f32_e32 v213, 0xbfb8aa3b, v71
	v_mul_f32_e32 v214, 0xbfb8aa3b, v72
	v_mul_f32_e32 v215, 0xbfb8aa3b, v73
	v_exp_f32_e32 v208, v208
	v_exp_f32_e32 v209, v209
	v_exp_f32_e32 v210, v210
	v_exp_f32_e32 v211, v211
	v_exp_f32_e32 v212, v212
	v_exp_f32_e32 v213, v213
	v_exp_f32_e32 v214, v214
	v_exp_f32_e32 v215, v215
	v_add_f32_e32 v208, 1.0, v208
	v_add_f32_e32 v209, 1.0, v209
	v_add_f32_e32 v210, 1.0, v210
	v_add_f32_e32 v211, 1.0, v211
	v_add_f32_e32 v212, 1.0, v212
	v_add_f32_e32 v213, 1.0, v213
	v_add_f32_e32 v214, 1.0, v214
	v_add_f32_e32 v215, 1.0, v215
	v_rcp_f32_e32 v208, v208
	v_rcp_f32_e32 v209, v209
	v_rcp_f32_e32 v210, v210
	v_rcp_f32_e32 v211, v211
	v_rcp_f32_e32 v212, v212
	v_rcp_f32_e32 v213, v213
	v_rcp_f32_e32 v214, v214
	v_rcp_f32_e32 v215, v215
	v_mul_f32_e32 v216, v78, v208
	v_mul_f32_e32 v217, v79, v209
	v_mul_f32_e32 v218, v80, v210
	v_mul_f32_e32 v219, v81, v211
	v_mul_f32_e32 v220, v70, v212
	v_mul_f32_e32 v221, v71, v213
	v_mul_f32_e32 v222, v72, v214
	v_mul_f32_e32 v223, v73, v215
	v_mul_f32_e32 v216, v216, v74
	v_mul_f32_e32 v217, v217, v75
	v_mul_f32_e32 v218, v218, v76
	v_mul_f32_e32 v219, v219, v77
	v_mul_f32_e32 v220, v220, v66
	v_mul_f32_e32 v221, v221, v67
	v_mul_f32_e32 v222, v222, v68
	v_mul_f32_e32 v223, v223, v69
	v_or_b32_e32 v82, 48, v146
	v_mad_i64_i32 v[82:83], s[16:17], v82, s65, v[140:141]
	v_lshl_add_u64 v[70:71], v[82:83], 0, v[114:115]
	v_cvt_pk_bf16_f32 v66, v216, v217
	v_cvt_pk_bf16_f32 v67, v218, v219
	v_cvt_pk_bf16_f32 v68, v220, v221
	v_cvt_pk_bf16_f32 v69, v222, v223
	global_store_dwordx4 v[70:71], v[66:69], off
	v_mul_f32_e32 v208, 0xbfb8aa3b, v62
	v_mul_f32_e32 v209, 0xbfb8aa3b, v63
	v_mul_f32_e32 v210, 0xbfb8aa3b, v64
	v_mul_f32_e32 v211, 0xbfb8aa3b, v65
	v_mul_f32_e32 v212, 0xbfb8aa3b, v54
	v_mul_f32_e32 v213, 0xbfb8aa3b, v55
	v_mul_f32_e32 v214, 0xbfb8aa3b, v56
	v_mul_f32_e32 v215, 0xbfb8aa3b, v57
	v_exp_f32_e32 v208, v208
	v_exp_f32_e32 v209, v209
	v_exp_f32_e32 v210, v210
	v_exp_f32_e32 v211, v211
	v_exp_f32_e32 v212, v212
	v_exp_f32_e32 v213, v213
	v_exp_f32_e32 v214, v214
	v_exp_f32_e32 v215, v215
	v_add_f32_e32 v208, 1.0, v208
	v_add_f32_e32 v209, 1.0, v209
	v_add_f32_e32 v210, 1.0, v210
	v_add_f32_e32 v211, 1.0, v211
	v_add_f32_e32 v212, 1.0, v212
	v_add_f32_e32 v213, 1.0, v213
	v_add_f32_e32 v214, 1.0, v214
	v_add_f32_e32 v215, 1.0, v215
	v_rcp_f32_e32 v208, v208
	v_rcp_f32_e32 v209, v209
	v_rcp_f32_e32 v210, v210
	v_rcp_f32_e32 v211, v211
	v_rcp_f32_e32 v212, v212
	v_rcp_f32_e32 v213, v213
	v_rcp_f32_e32 v214, v214
	v_rcp_f32_e32 v215, v215
	v_mul_f32_e32 v216, v62, v208
	v_mul_f32_e32 v217, v63, v209
	v_mul_f32_e32 v218, v64, v210
	v_mul_f32_e32 v219, v65, v211
	v_mul_f32_e32 v220, v54, v212
	v_mul_f32_e32 v221, v55, v213
	v_mul_f32_e32 v222, v56, v214
	v_mul_f32_e32 v223, v57, v215
	v_mul_f32_e32 v216, v216, v58
	v_mul_f32_e32 v217, v217, v59
	v_mul_f32_e32 v218, v218, v60
	v_mul_f32_e32 v219, v219, v61
	v_mul_f32_e32 v220, v220, v50
	v_mul_f32_e32 v221, v221, v51
	v_mul_f32_e32 v222, v222, v52
	v_mul_f32_e32 v223, v223, v53
	v_add_u32_e32 v66, 0x80, v146
	v_mad_i64_i32 v[66:67], s[16:17], v66, s65, v[140:141]
	v_lshl_add_u64 v[54:55], v[66:67], 0, v[114:115]
	v_cvt_pk_bf16_f32 v50, v216, v217
	v_cvt_pk_bf16_f32 v51, v218, v219
	v_cvt_pk_bf16_f32 v52, v220, v221
	v_cvt_pk_bf16_f32 v53, v222, v223
	global_store_dwordx4 v[54:55], v[50:53], off
	v_mul_f32_e32 v208, 0xbfb8aa3b, v46
	v_mul_f32_e32 v209, 0xbfb8aa3b, v47
	v_mul_f32_e32 v210, 0xbfb8aa3b, v48
	v_mul_f32_e32 v211, 0xbfb8aa3b, v49
	v_mul_f32_e32 v212, 0xbfb8aa3b, v38
	v_mul_f32_e32 v213, 0xbfb8aa3b, v39
	v_mul_f32_e32 v214, 0xbfb8aa3b, v40
	v_mul_f32_e32 v215, 0xbfb8aa3b, v41
	v_exp_f32_e32 v208, v208
	v_exp_f32_e32 v209, v209
	v_exp_f32_e32 v210, v210
	v_exp_f32_e32 v211, v211
	v_exp_f32_e32 v212, v212
	v_exp_f32_e32 v213, v213
	v_exp_f32_e32 v214, v214
	v_exp_f32_e32 v215, v215
	v_add_f32_e32 v208, 1.0, v208
	v_add_f32_e32 v209, 1.0, v209
	v_add_f32_e32 v210, 1.0, v210
	v_add_f32_e32 v211, 1.0, v211
	v_add_f32_e32 v212, 1.0, v212
	v_add_f32_e32 v213, 1.0, v213
	v_add_f32_e32 v214, 1.0, v214
	v_add_f32_e32 v215, 1.0, v215
	v_rcp_f32_e32 v208, v208
	v_rcp_f32_e32 v209, v209
	v_rcp_f32_e32 v210, v210
	v_rcp_f32_e32 v211, v211
	v_rcp_f32_e32 v212, v212
	v_rcp_f32_e32 v213, v213
	v_rcp_f32_e32 v214, v214
	v_rcp_f32_e32 v215, v215
	v_mul_f32_e32 v216, v46, v208
	v_mul_f32_e32 v217, v47, v209
	v_mul_f32_e32 v218, v48, v210
	v_mul_f32_e32 v219, v49, v211
	v_mul_f32_e32 v220, v38, v212
	v_mul_f32_e32 v221, v39, v213
	v_mul_f32_e32 v222, v40, v214
	v_mul_f32_e32 v223, v41, v215
	v_mul_f32_e32 v216, v216, v42
	v_mul_f32_e32 v217, v217, v43
	v_mul_f32_e32 v218, v218, v44
	v_mul_f32_e32 v219, v219, v45
	v_mul_f32_e32 v220, v220, v34
	v_mul_f32_e32 v221, v221, v35
	v_mul_f32_e32 v222, v222, v36
	v_mul_f32_e32 v223, v223, v37
	v_add_u32_e32 v50, 0x90, v146
	v_mad_i64_i32 v[50:51], s[16:17], v50, s65, v[140:141]
	v_lshl_add_u64 v[38:39], v[50:51], 0, v[114:115]
	v_cvt_pk_bf16_f32 v34, v216, v217
	v_cvt_pk_bf16_f32 v35, v218, v219
	v_cvt_pk_bf16_f32 v36, v220, v221
	v_cvt_pk_bf16_f32 v37, v222, v223
	global_store_dwordx4 v[38:39], v[34:37], off
	v_mul_f32_e32 v208, 0xbfb8aa3b, v30
	v_mul_f32_e32 v209, 0xbfb8aa3b, v31
	v_mul_f32_e32 v210, 0xbfb8aa3b, v32
	v_mul_f32_e32 v211, 0xbfb8aa3b, v33
	v_mul_f32_e32 v212, 0xbfb8aa3b, v22
	v_mul_f32_e32 v213, 0xbfb8aa3b, v23
	v_mul_f32_e32 v214, 0xbfb8aa3b, v24
	v_mul_f32_e32 v215, 0xbfb8aa3b, v25
	v_exp_f32_e32 v208, v208
	v_exp_f32_e32 v209, v209
	v_exp_f32_e32 v210, v210
	v_exp_f32_e32 v211, v211
	v_exp_f32_e32 v212, v212
	v_exp_f32_e32 v213, v213
	v_exp_f32_e32 v214, v214
	v_exp_f32_e32 v215, v215
	v_add_f32_e32 v208, 1.0, v208
	v_add_f32_e32 v209, 1.0, v209
	v_add_f32_e32 v210, 1.0, v210
	v_add_f32_e32 v211, 1.0, v211
	v_add_f32_e32 v212, 1.0, v212
	v_add_f32_e32 v213, 1.0, v213
	v_add_f32_e32 v214, 1.0, v214
	v_add_f32_e32 v215, 1.0, v215
	v_rcp_f32_e32 v208, v208
	v_rcp_f32_e32 v209, v209
	v_rcp_f32_e32 v210, v210
	v_rcp_f32_e32 v211, v211
	v_rcp_f32_e32 v212, v212
	v_rcp_f32_e32 v213, v213
	v_rcp_f32_e32 v214, v214
	v_rcp_f32_e32 v215, v215
	v_mul_f32_e32 v216, v30, v208
	v_mul_f32_e32 v217, v31, v209
	v_mul_f32_e32 v218, v32, v210
	v_mul_f32_e32 v219, v33, v211
	v_mul_f32_e32 v220, v22, v212
	v_mul_f32_e32 v221, v23, v213
	v_mul_f32_e32 v222, v24, v214
	v_mul_f32_e32 v223, v25, v215
	v_mul_f32_e32 v216, v216, v26
	v_mul_f32_e32 v217, v217, v27
	v_mul_f32_e32 v218, v218, v28
	v_mul_f32_e32 v219, v219, v29
	v_mul_f32_e32 v220, v220, v18
	v_mul_f32_e32 v221, v221, v19
	v_mul_f32_e32 v222, v222, v20
	v_mul_f32_e32 v223, v223, v21
	v_add_u32_e32 v34, 0xa0, v146
	v_mad_i64_i32 v[34:35], s[16:17], v34, s65, v[140:141]
	v_lshl_add_u64 v[22:23], v[34:35], 0, v[114:115]
	v_cvt_pk_bf16_f32 v18, v216, v217
	v_cvt_pk_bf16_f32 v19, v218, v219
	v_cvt_pk_bf16_f32 v20, v220, v221
	v_cvt_pk_bf16_f32 v21, v222, v223
	global_store_dwordx4 v[22:23], v[18:21], off
	v_mul_f32_e32 v208, 0xbfb8aa3b, v12
	v_mul_f32_e32 v209, 0xbfb8aa3b, v13
	v_mul_f32_e32 v210, 0xbfb8aa3b, v14
	v_mul_f32_e32 v211, 0xbfb8aa3b, v15
	v_mul_f32_e32 v212, 0xbfb8aa3b, v4
	v_mul_f32_e32 v213, 0xbfb8aa3b, v5
	v_mul_f32_e32 v214, 0xbfb8aa3b, v6
	v_mul_f32_e32 v215, 0xbfb8aa3b, v7
	v_exp_f32_e32 v208, v208
	v_exp_f32_e32 v209, v209
	v_exp_f32_e32 v210, v210
	v_exp_f32_e32 v211, v211
	v_exp_f32_e32 v212, v212
	v_exp_f32_e32 v213, v213
	v_exp_f32_e32 v214, v214
	v_exp_f32_e32 v215, v215
	v_add_f32_e32 v208, 1.0, v208
	v_add_f32_e32 v209, 1.0, v209
	v_add_f32_e32 v210, 1.0, v210
	v_add_f32_e32 v211, 1.0, v211
	v_add_f32_e32 v212, 1.0, v212
	v_add_f32_e32 v213, 1.0, v213
	v_add_f32_e32 v214, 1.0, v214
	v_add_f32_e32 v215, 1.0, v215
	v_rcp_f32_e32 v208, v208
	v_rcp_f32_e32 v209, v209
	v_rcp_f32_e32 v210, v210
	v_rcp_f32_e32 v211, v211
	v_rcp_f32_e32 v212, v212
	v_rcp_f32_e32 v213, v213
	v_rcp_f32_e32 v214, v214
	v_rcp_f32_e32 v215, v215
	v_mul_f32_e32 v216, v12, v208
	v_mul_f32_e32 v217, v13, v209
	v_mul_f32_e32 v218, v14, v210
	v_mul_f32_e32 v219, v15, v211
	v_mul_f32_e32 v220, v4, v212
	v_mul_f32_e32 v221, v5, v213
	v_mul_f32_e32 v222, v6, v214
	v_mul_f32_e32 v223, v7, v215
	v_mul_f32_e32 v216, v216, v8
	v_mul_f32_e32 v217, v217, v9
	v_mul_f32_e32 v218, v218, v10
	v_mul_f32_e32 v219, v219, v11
	v_mul_f32_e32 v220, v220, v0
	v_mul_f32_e32 v221, v221, v1
	v_mul_f32_e32 v222, v222, v2
	v_mul_f32_e32 v223, v223, v3
	v_add_u32_e32 v18, 0xb0, v146
	v_mad_i64_i32 v[18:19], s[16:17], v18, s65, v[140:141]
	v_lshl_add_u64 v[4:5], v[18:19], 0, v[114:115]
	v_cvt_pk_bf16_f32 v0, v216, v217
	v_cvt_pk_bf16_f32 v1, v218, v219
	v_cvt_pk_bf16_f32 v2, v220, v221
	v_cvt_pk_bf16_f32 v3, v222, v223
	global_store_dwordx4 v[4:5], v[0:3], off
	s_and_b64 vcc, exec, s[38:39]
	s_mov_b32 s2, s8
	s_mov_b32 s14, s28
	s_mov_b64 s[16:17], s[42:43]
	s_mov_b64 s[18:19], s[40:41]
	s_cbranch_vccz .LBB0_144
	s_waitcnt vmcnt(0)
	s_cmpk_gt_u32 s48, 0xff
	s_cbranch_scc1 .LBB0_151
	s_barrier

.LBB0_174:
	s_add_u32 s40, s22, 0x100
	s_addc_u32 s41, s23, 0
	s_add_i32 s83, 0, 0x10000
	v_add_u32_e32 v148, s83, v157
	ds_read_b128 v[130:133], v148
	ds_read_b128 v[134:137], v148 offset:1024
	ds_read_b128 v[138:141], v148 offset:2048
	ds_read_b128 v[148:151], v148 offset:3072
	s_cmp_eq_u32 s82, 12
	s_cselect_b32 s49, s9, s41
	s_cselect_b32 s48, s12, s40
	s_cselect_b32 s43, s5, s79
	s_cselect_b32 s42, s34, s61
	v_lshl_add_u64 v[188:189], s[22:23], 0, v[146:147]
	s_add_i32 m0, s19, 0xc000
	ds_read_b128 v[152:155], v159
	ds_read_b128 v[160:163], v159 offset:1024
	ds_read_b128 v[164:167], v159 offset:2048
	ds_read_b128 v[168:171], v159 offset:3072
	ds_read_b128 v[172:175], v159 offset:4096
	ds_read_b128 v[176:179], v159 offset:5120
	ds_read_b128 v[180:183], v159 offset:6144
	ds_read_b128 v[184:187], v159 offset:7168
	global_load_lds_dwordx4 v[188:189], off
	v_lshl_add_u64 v[188:189], s[22:23], 0, v[144:145]
	s_add_i32 m0, s19, 0xe000
	s_nop 0
	global_load_lds_dwordx4 v[188:189], off
	s_waitcnt lgkmcnt(8)
	s_waitcnt vmcnt(10)
	s_barrier
	s_waitcnt lgkmcnt(0)
	s_waitcnt lgkmcnt(0)
	v_mfma_f32_16x16x32_bf16 v[126:129], v[130:133], v[152:155], v[126:129]
	v_mfma_f32_16x16x32_bf16 v[122:125], v[138:141], v[152:155], v[122:125]
	v_mfma_f32_16x16x32_bf16 v[118:121], v[130:133], v[164:167], v[118:121]
	v_mfma_f32_16x16x32_bf16 v[106:109], v[138:141], v[164:167], v[106:109]
	v_mfma_f32_16x16x32_bf16 v[102:105], v[130:133], v[172:175], v[102:105]
	v_mfma_f32_16x16x32_bf16 v[90:93], v[138:141], v[172:175], v[90:93]
	v_mfma_f32_16x16x32_bf16 v[86:89], v[130:133], v[180:183], v[86:89]
	v_mfma_f32_16x16x32_bf16 v[74:77], v[138:141], v[180:183], v[74:77]
	v_mfma_f32_16x16x32_bf16 v[126:129], v[134:137], v[160:163], v[126:129]
	v_mfma_f32_16x16x32_bf16 v[122:125], v[148:151], v[160:163], v[122:125]
	v_mfma_f32_16x16x32_bf16 v[118:121], v[134:137], v[168:171], v[118:121]
	v_mfma_f32_16x16x32_bf16 v[106:109], v[148:151], v[168:171], v[106:109]
	v_mfma_f32_16x16x32_bf16 v[102:105], v[134:137], v[176:179], v[102:105]
	v_mfma_f32_16x16x32_bf16 v[90:93], v[148:151], v[176:179], v[90:93]
	v_mfma_f32_16x16x32_bf16 v[86:89], v[134:137], v[184:187], v[86:89]
	v_mfma_f32_16x16x32_bf16 v[74:77], v[148:151], v[184:187], v[74:77]
	s_barrier
	s_add_i32 s84, 0, 0x14000
	v_add_u32_e32 v196, s84, v157
	s_add_i32 s22, s83, s52
	ds_read_b128 v[188:191], v196
	ds_read_b128 v[192:195], v196 offset:1024
	ds_read_b128 v[208:211], v196 offset:2048
	ds_read_b128 v[212:215], v196 offset:3072
	v_lshl_add_u64 v[196:197], s[42:43], 0, v[16:17]
	s_mov_b32 m0, s22
	v_lshl_add_u64 v[216:217], s[42:43], 0, v[142:143]
	global_load_lds_dwordx4 v[196:197], off
	s_add_i32 m0, s22, 0x2000
	s_nop 0
	global_load_lds_dwordx4 v[216:217], off
	s_waitcnt vmcnt(10)
	s_barrier
	s_waitcnt lgkmcnt(0)
	s_waitcnt lgkmcnt(0)
	v_mfma_f32_16x16x32_bf16 v[114:117], v[188:191], v[152:155], v[114:117]
	v_mfma_f32_16x16x32_bf16 v[110:113], v[208:211], v[152:155], v[110:113]
	v_mfma_f32_16x16x32_bf16 v[98:101], v[188:191], v[164:167], v[98:101]
	v_mfma_f32_16x16x32_bf16 v[94:97], v[208:211], v[164:167], v[94:97]
	v_mfma_f32_16x16x32_bf16 v[82:85], v[188:191], v[172:175], v[82:85]
	v_mfma_f32_16x16x32_bf16 v[78:81], v[208:211], v[172:175], v[78:81]
	v_mfma_f32_16x16x32_bf16 v[70:73], v[188:191], v[180:183], v[70:73]
	v_mfma_f32_16x16x32_bf16 v[66:69], v[208:211], v[180:183], v[66:69]
	v_mfma_f32_16x16x32_bf16 v[114:117], v[192:195], v[160:163], v[114:117]
	v_mfma_f32_16x16x32_bf16 v[110:113], v[212:215], v[160:163], v[110:113]
	v_mfma_f32_16x16x32_bf16 v[98:101], v[192:195], v[168:171], v[98:101]
	v_mfma_f32_16x16x32_bf16 v[94:97], v[212:215], v[168:171], v[94:97]
	v_mfma_f32_16x16x32_bf16 v[82:85], v[192:195], v[176:179], v[82:85]
	v_mfma_f32_16x16x32_bf16 v[78:81], v[212:215], v[176:179], v[78:81]
	v_mfma_f32_16x16x32_bf16 v[70:73], v[192:195], v[184:187], v[70:73]
	v_mfma_f32_16x16x32_bf16 v[66:69], v[212:215], v[184:187], v[66:69]
	s_mov_b32 m0, s19
	v_lshl_add_u64 v[218:219], s[48:49], 0, v[16:17]
	s_barrier
	ds_read_b128 v[152:155], v159 offset:16384
	ds_read_b128 v[160:163], v159 offset:17408
	ds_read_b128 v[164:167], v159 offset:18432
	ds_read_b128 v[168:171], v159 offset:19456
	ds_read_b128 v[172:175], v159 offset:20480
	ds_read_b128 v[176:179], v159 offset:21504
	ds_read_b128 v[180:183], v159 offset:22528
	ds_read_b128 v[184:187], v159 offset:23552
	global_load_lds_dwordx4 v[218:219], off
	v_lshl_add_u64 v[220:221], s[48:49], 0, v[142:143]
	s_mov_b32 m0, s54
	s_nop 0
	global_load_lds_dwordx4 v[220:221], off
	s_barrier
	s_waitcnt lgkmcnt(0)
	s_waitcnt lgkmcnt(0)
	v_mfma_f32_16x16x32_bf16 v[62:65], v[130:133], v[152:155], v[62:65]
	v_mfma_f32_16x16x32_bf16 v[58:61], v[138:141], v[152:155], v[58:61]
	v_mfma_f32_16x16x32_bf16 v[54:57], v[130:133], v[164:167], v[54:57]
	v_mfma_f32_16x16x32_bf16 v[50:53], v[138:141], v[164:167], v[50:53]
	v_mfma_f32_16x16x32_bf16 v[46:49], v[130:133], v[172:175], v[46:49]
	v_mfma_f32_16x16x32_bf16 v[38:41], v[138:141], v[172:175], v[38:41]
	v_mfma_f32_16x16x32_bf16 v[30:33], v[130:133], v[180:183], v[30:33]
	v_mfma_f32_16x16x32_bf16 v[18:21], v[138:141], v[180:183], v[18:21]
	v_mfma_f32_16x16x32_bf16 v[62:65], v[134:137], v[160:163], v[62:65]
	v_mfma_f32_16x16x32_bf16 v[58:61], v[148:151], v[160:163], v[58:61]
	v_mfma_f32_16x16x32_bf16 v[54:57], v[134:137], v[168:171], v[54:57]
	v_mfma_f32_16x16x32_bf16 v[50:53], v[148:151], v[168:171], v[50:53]
	v_mfma_f32_16x16x32_bf16 v[46:49], v[134:137], v[176:179], v[46:49]
	v_mfma_f32_16x16x32_bf16 v[38:41], v[148:151], v[176:179], v[38:41]
	v_mfma_f32_16x16x32_bf16 v[30:33], v[134:137], v[184:187], v[30:33]
	v_mfma_f32_16x16x32_bf16 v[18:21], v[148:151], v[184:187], v[18:21]
	s_barrier
	s_add_u32 s22, s42, 0x40000
	s_addc_u32 s23, s43, 0
	s_add_i32 s83, s84, s52
	v_lshl_add_u64 v[130:131], s[22:23], 0, v[16:17]
	s_mov_b32 m0, s83
	s_nop 0
	global_load_lds_dwordx4 v[130:131], off
	v_lshl_add_u64 v[130:131], s[22:23], 0, v[142:143]
	s_add_i32 m0, s83, 0x2000
	s_nop 0
	global_load_lds_dwordx4 v[130:131], off
	s_waitcnt vmcnt(10)
	s_barrier
	v_mfma_f32_16x16x32_bf16 v[42:45], v[188:191], v[152:155], v[42:45]
	v_mfma_f32_16x16x32_bf16 v[34:37], v[208:211], v[152:155], v[34:37]
	v_mfma_f32_16x16x32_bf16 v[26:29], v[188:191], v[164:167], v[26:29]
	v_mfma_f32_16x16x32_bf16 v[22:25], v[208:211], v[164:167], v[22:25]
	v_mfma_f32_16x16x32_bf16 v[12:15], v[188:191], v[172:175], v[12:15]
	v_mfma_f32_16x16x32_bf16 v[8:11], v[208:211], v[172:175], v[8:11]
	v_mfma_f32_16x16x32_bf16 v[4:7], v[188:191], v[180:183], v[4:7]
	v_mfma_f32_16x16x32_bf16 v[0:3], v[208:211], v[180:183], v[0:3]
	v_mfma_f32_16x16x32_bf16 v[42:45], v[192:195], v[160:163], v[42:45]
	v_mfma_f32_16x16x32_bf16 v[34:37], v[212:215], v[160:163], v[34:37]
	v_mfma_f32_16x16x32_bf16 v[26:29], v[192:195], v[168:171], v[26:29]
	v_mfma_f32_16x16x32_bf16 v[22:25], v[212:215], v[168:171], v[22:25]
	v_mfma_f32_16x16x32_bf16 v[12:15], v[192:195], v[176:179], v[12:15]
	v_mfma_f32_16x16x32_bf16 v[8:11], v[212:215], v[176:179], v[8:11]
	v_mfma_f32_16x16x32_bf16 v[4:7], v[192:195], v[184:187], v[4:7]
	v_mfma_f32_16x16x32_bf16 v[0:3], v[212:215], v[184:187], v[0:3]
	s_add_i32 s83, 0, 0x18000
	v_add_u32_e32 v148, s83, v157
	s_barrier
	ds_read_b128 v[130:133], v148
	ds_read_b128 v[134:137], v148 offset:1024
	ds_read_b128 v[138:141], v148 offset:2048
	ds_read_b128 v[148:151], v148 offset:3072
	s_add_u32 s22, s48, 0x40000
	s_addc_u32 s23, s49, 0
	s_mov_b32 m0, s55
	v_lshl_add_u64 v[188:189], s[22:23], 0, v[16:17]
	ds_read_b128 v[152:155], v159 offset:32768
	ds_read_b128 v[160:163], v159 offset:33792
	ds_read_b128 v[164:167], v159 offset:34816
	ds_read_b128 v[168:171], v159 offset:35840
	ds_read_b128 v[172:175], v159 offset:36864
	ds_read_b128 v[176:179], v159 offset:37888
	ds_read_b128 v[180:183], v159 offset:38912
	ds_read_b128 v[184:187], v159 offset:39936
	global_load_lds_dwordx4 v[188:189], off
	v_lshl_add_u64 v[188:189], s[22:23], 0, v[142:143]
	s_mov_b32 m0, s56
	s_nop 0
	global_load_lds_dwordx4 v[188:189], off
	s_waitcnt lgkmcnt(8)
	s_waitcnt vmcnt(10)
	s_barrier
	s_waitcnt lgkmcnt(0)
	s_waitcnt lgkmcnt(0)
	v_mfma_f32_16x16x32_bf16 v[126:129], v[130:133], v[152:155], v[126:129]
	v_mfma_f32_16x16x32_bf16 v[122:125], v[138:141], v[152:155], v[122:125]
	v_mfma_f32_16x16x32_bf16 v[118:121], v[130:133], v[164:167], v[118:121]
	v_mfma_f32_16x16x32_bf16 v[106:109], v[138:141], v[164:167], v[106:109]
	v_mfma_f32_16x16x32_bf16 v[102:105], v[130:133], v[172:175], v[102:105]
	v_mfma_f32_16x16x32_bf16 v[90:93], v[138:141], v[172:175], v[90:93]
	v_mfma_f32_16x16x32_bf16 v[86:89], v[130:133], v[180:183], v[86:89]
	v_mfma_f32_16x16x32_bf16 v[74:77], v[138:141], v[180:183], v[74:77]
	v_mfma_f32_16x16x32_bf16 v[126:129], v[134:137], v[160:163], v[126:129]
	v_mfma_f32_16x16x32_bf16 v[122:125], v[148:151], v[160:163], v[122:125]
	v_mfma_f32_16x16x32_bf16 v[118:121], v[134:137], v[168:171], v[118:121]
	v_mfma_f32_16x16x32_bf16 v[106:109], v[148:151], v[168:171], v[106:109]
	v_mfma_f32_16x16x32_bf16 v[102:105], v[134:137], v[176:179], v[102:105]
	v_mfma_f32_16x16x32_bf16 v[90:93], v[148:151], v[176:179], v[90:93]
	v_mfma_f32_16x16x32_bf16 v[86:89], v[134:137], v[184:187], v[86:89]
	v_mfma_f32_16x16x32_bf16 v[74:77], v[148:151], v[184:187], v[74:77]
	s_barrier
	s_add_i32 s48, 0, 0x1c000
	s_add_i32 s22, s83, s52
	v_add_u32_e32 v212, s48, v157
	v_lshl_add_u64 v[196:197], v[196:197], 0, s[10:11]
	s_mov_b32 m0, s22
	ds_read_b128 v[188:191], v212
	ds_read_b128 v[192:195], v212 offset:1024
	ds_read_b128 v[208:211], v212 offset:2048
	ds_read_b128 v[212:215], v212 offset:3072
	global_load_lds_dwordx4 v[196:197], off
	v_lshl_add_u64 v[196:197], v[216:217], 0, s[10:11]
	s_add_i32 m0, s22, 0x2000
	s_nop 0
	global_load_lds_dwordx4 v[196:197], off
	s_waitcnt vmcnt(10)
	s_barrier
	s_waitcnt lgkmcnt(0)
	s_waitcnt lgkmcnt(0)
	v_mfma_f32_16x16x32_bf16 v[114:117], v[188:191], v[152:155], v[114:117]
	v_mfma_f32_16x16x32_bf16 v[110:113], v[208:211], v[152:155], v[110:113]
	v_mfma_f32_16x16x32_bf16 v[98:101], v[188:191], v[164:167], v[98:101]
	v_mfma_f32_16x16x32_bf16 v[94:97], v[208:211], v[164:167], v[94:97]
	v_mfma_f32_16x16x32_bf16 v[82:85], v[188:191], v[172:175], v[82:85]
	v_mfma_f32_16x16x32_bf16 v[78:81], v[208:211], v[172:175], v[78:81]
	v_mfma_f32_16x16x32_bf16 v[70:73], v[188:191], v[180:183], v[70:73]
	v_mfma_f32_16x16x32_bf16 v[66:69], v[208:211], v[180:183], v[66:69]
	v_mfma_f32_16x16x32_bf16 v[114:117], v[192:195], v[160:163], v[114:117]
	v_mfma_f32_16x16x32_bf16 v[110:113], v[212:215], v[160:163], v[110:113]
	v_mfma_f32_16x16x32_bf16 v[98:101], v[192:195], v[168:171], v[98:101]
	v_mfma_f32_16x16x32_bf16 v[94:97], v[212:215], v[168:171], v[94:97]
	v_mfma_f32_16x16x32_bf16 v[82:85], v[192:195], v[176:179], v[82:85]
	v_mfma_f32_16x16x32_bf16 v[78:81], v[212:215], v[176:179], v[78:81]
	v_mfma_f32_16x16x32_bf16 v[70:73], v[192:195], v[184:187], v[70:73]
	v_mfma_f32_16x16x32_bf16 v[66:69], v[212:215], v[184:187], v[66:69]
	s_mov_b32 m0, s57
	v_lshl_add_u64 v[196:197], v[218:219], 0, s[10:11]
	s_barrier
	ds_read_b128 v[152:155], v159 offset:49152
	ds_read_b128 v[160:163], v159 offset:50176
	ds_read_b128 v[164:167], v159 offset:51200
	ds_read_b128 v[168:171], v159 offset:52224
	ds_read_b128 v[172:175], v159 offset:53248
	ds_read_b128 v[176:179], v159 offset:54272
	ds_read_b128 v[180:183], v159 offset:55296
	ds_read_b128 v[184:187], v159 offset:56320
	global_load_lds_dwordx4 v[196:197], off
	v_lshl_add_u64 v[196:197], v[220:221], 0, s[10:11]
	s_mov_b32 m0, s58
	s_nop 0
	global_load_lds_dwordx4 v[196:197], off
	s_barrier
	s_waitcnt lgkmcnt(0)
	s_waitcnt lgkmcnt(0)
	v_mfma_f32_16x16x32_bf16 v[62:65], v[130:133], v[152:155], v[62:65]
	v_mfma_f32_16x16x32_bf16 v[58:61], v[138:141], v[152:155], v[58:61]
	v_mfma_f32_16x16x32_bf16 v[54:57], v[130:133], v[164:167], v[54:57]
	v_mfma_f32_16x16x32_bf16 v[50:53], v[138:141], v[164:167], v[50:53]
	v_mfma_f32_16x16x32_bf16 v[46:49], v[130:133], v[172:175], v[46:49]
	v_mfma_f32_16x16x32_bf16 v[38:41], v[138:141], v[172:175], v[38:41]
	v_mfma_f32_16x16x32_bf16 v[30:33], v[130:133], v[180:183], v[30:33]
	v_mfma_f32_16x16x32_bf16 v[18:21], v[138:141], v[180:183], v[18:21]
	v_mfma_f32_16x16x32_bf16 v[62:65], v[134:137], v[160:163], v[62:65]
	v_mfma_f32_16x16x32_bf16 v[58:61], v[148:151], v[160:163], v[58:61]
	v_mfma_f32_16x16x32_bf16 v[54:57], v[134:137], v[168:171], v[54:57]
	v_mfma_f32_16x16x32_bf16 v[50:53], v[148:151], v[168:171], v[50:53]
	v_mfma_f32_16x16x32_bf16 v[46:49], v[134:137], v[176:179], v[46:49]
	v_mfma_f32_16x16x32_bf16 v[38:41], v[148:151], v[176:179], v[38:41]
	v_mfma_f32_16x16x32_bf16 v[30:33], v[134:137], v[184:187], v[30:33]
	v_mfma_f32_16x16x32_bf16 v[18:21], v[148:151], v[184:187], v[18:21]
	s_barrier
	s_add_u32 s22, s42, 0x40080
	s_addc_u32 s23, s43, 0
	s_add_i32 s42, s48, s52
	v_lshl_add_u64 v[130:131], s[22:23], 0, v[16:17]
	s_mov_b32 m0, s42
	s_nop 0
	global_load_lds_dwordx4 v[130:131], off
	v_lshl_add_u64 v[130:131], s[22:23], 0, v[142:143]
	s_add_i32 m0, s42, 0x2000
	s_nop 0
	global_load_lds_dwordx4 v[130:131], off
	s_waitcnt vmcnt(10)
	s_barrier
	v_mfma_f32_16x16x32_bf16 v[42:45], v[188:191], v[152:155], v[42:45]
	v_mfma_f32_16x16x32_bf16 v[34:37], v[208:211], v[152:155], v[34:37]
	v_mfma_f32_16x16x32_bf16 v[26:29], v[188:191], v[164:167], v[26:29]
	v_mfma_f32_16x16x32_bf16 v[22:25], v[208:211], v[164:167], v[22:25]
	v_mfma_f32_16x16x32_bf16 v[12:15], v[188:191], v[172:175], v[12:15]
	v_mfma_f32_16x16x32_bf16 v[8:11], v[208:211], v[172:175], v[8:11]
	v_mfma_f32_16x16x32_bf16 v[4:7], v[188:191], v[180:183], v[4:7]
	v_mfma_f32_16x16x32_bf16 v[0:3], v[208:211], v[180:183], v[0:3]
	v_mfma_f32_16x16x32_bf16 v[42:45], v[192:195], v[160:163], v[42:45]
	v_mfma_f32_16x16x32_bf16 v[34:37], v[212:215], v[160:163], v[34:37]
	v_mfma_f32_16x16x32_bf16 v[26:29], v[192:195], v[168:171], v[26:29]
	v_mfma_f32_16x16x32_bf16 v[22:25], v[212:215], v[168:171], v[22:25]
	v_mfma_f32_16x16x32_bf16 v[12:15], v[192:195], v[176:179], v[12:15]
	v_mfma_f32_16x16x32_bf16 v[8:11], v[212:215], v[176:179], v[8:11]
	v_mfma_f32_16x16x32_bf16 v[4:7], v[192:195], v[184:187], v[4:7]
	v_mfma_f32_16x16x32_bf16 v[0:3], v[212:215], v[184:187], v[0:3]
	s_add_i32 s82, s82, 2
	s_add_u32 s61, s61, 0x100
	s_addc_u32 s79, s79, 0
	s_cmp_gt_u32 s82, 13
	s_mov_b64 s[22:23], s[40:41]
	s_barrier
	s_cbranch_scc0 .LBB0_174
	v_lshl_or_b32 v132, s2, 8, v158
	v_lshl_add_u32 v130, s18, 8, v156
	v_ashrrev_i32_e32 v133, 31, v132
	v_lshlrev_b64 v[148:149], 2, v[132:133]
	v_ashrrev_i32_e32 v131, 31, v130
	v_lshl_add_u64 v[150:151], s[20:21], 0, v[148:149]
	v_lshlrev_b64 v[152:153], 12, v[130:131]
	v_lshl_add_u64 v[132:133], v[150:151], 0, v[152:153]
	global_load_dwordx4 v[160:163], v[132:133], off
	global_load_dwordx4 v[164:167], v[132:133], off offset:64
	global_load_dwordx4 v[168:171], v[132:133], off offset:512
	global_load_dwordx4 v[172:175], v[132:133], off offset:576
	v_or_b32_e32 v132, 16, v130
	v_ashrrev_i32_e32 v133, 31, v132
	v_lshlrev_b64 v[196:197], 12, v[132:133]
	v_lshl_add_u64 v[132:133], v[150:151], 0, v[196:197]
	global_load_dwordx4 v[176:179], v[132:133], off
	global_load_dwordx4 v[180:183], v[132:133], off offset:64
	global_load_dwordx4 v[184:187], v[132:133], off offset:512
	global_load_dwordx4 v[188:191], v[132:133], off offset:576
	v_or_b32_e32 v132, 32, v130
	v_ashrrev_i32_e32 v133, 31, v132
	v_or_b32_e32 v130, 48, v130
	v_lshlrev_b64 v[224:225], 12, v[132:133]
	v_ashrrev_i32_e32 v131, 31, v130
	v_lshl_add_u64 v[132:133], v[150:151], 0, v[224:225]
	v_lshlrev_b64 v[154:155], 12, v[130:131]
	global_load_dwordx4 v[192:195], v[132:133], off
	global_load_dwordx4 v[208:211], v[132:133], off offset:64
	global_load_dwordx4 v[212:215], v[132:133], off offset:512
	global_load_dwordx4 v[216:219], v[132:133], off offset:576
	v_lshl_add_u64 v[130:131], v[150:151], 0, v[154:155]
	global_load_dwordx4 v[220:223], v[130:131], off
	global_load_dwordx4 v[138:141], v[130:131], off offset:64
	global_load_dwordx4 v[134:137], v[130:131], off offset:512
	s_nop 0
	global_load_dwordx4 v[130:133], v[130:131], off offset:576
	s_waitcnt vmcnt(0) lgkmcnt(0)
	v_pk_add_f32 v[126:127], v[126:127], v[160:161]
	v_lshl_add_u64 v[160:161], s[20:21], 0, v[152:153]
	v_lshl_add_u64 v[160:161], v[160:161], 0, v[148:149]
	v_pk_add_f32 v[116:117], v[116:117], v[170:171]
	v_pk_add_f32 v[114:115], v[114:115], v[168:169]
	global_store_dwordx4 v[160:161], v[114:117], off offset:512
	v_pk_add_f32 v[112:113], v[112:113], v[174:175]
	v_pk_add_f32 v[100:101], v[100:101], v[186:187]
	v_lshl_add_u64 v[114:115], s[20:21], 0, v[196:197]
	v_lshl_add_u64 v[114:115], v[114:115], 0, v[148:149]
	v_pk_add_f32 v[98:99], v[98:99], v[184:185]
	global_store_dwordx4 v[114:115], v[98:101], off offset:512
	v_pk_add_f32 v[110:111], v[110:111], v[172:173]
	v_pk_add_f32 v[96:97], v[96:97], v[190:191]
	v_lshl_add_u64 v[98:99], s[20:21], 0, v[224:225]
	v_lshl_add_u64 v[98:99], v[98:99], 0, v[148:149]
	v_pk_add_f32 v[84:85], v[84:85], v[214:215]
	v_pk_add_f32 v[82:83], v[82:83], v[212:213]
	v_pk_add_f32 v[94:95], v[94:95], v[188:189]
	global_store_dwordx4 v[98:99], v[82:85], off offset:512
	v_pk_add_f32 v[80:81], v[80:81], v[218:219]
	v_pk_add_f32 v[78:79], v[78:79], v[216:217]
	v_lshl_add_u64 v[82:83], s[20:21], 0, v[154:155]
	v_pk_add_f32 v[128:129], v[128:129], v[162:163]
	v_pk_add_f32 v[124:125], v[124:125], v[166:167]
	v_pk_add_f32 v[122:123], v[122:123], v[164:165]
	global_store_dwordx4 v[160:161], v[110:113], off offset:576
	v_pk_add_f32 v[108:109], v[108:109], v[182:183]
	v_pk_add_f32 v[106:107], v[106:107], v[180:181]
	v_pk_add_f32 v[112:113], v[120:121], v[178:179]
	v_pk_add_f32 v[110:111], v[118:119], v[176:177]
	global_store_dwordx4 v[114:115], v[94:97], off offset:576
	v_pk_add_f32 v[92:93], v[92:93], v[210:211]
	v_pk_add_f32 v[90:91], v[90:91], v[208:209]
	v_pk_add_f32 v[96:97], v[104:105], v[194:195]
	v_pk_add_f32 v[94:95], v[102:103], v[192:193]
	global_store_dwordx4 v[98:99], v[78:81], off offset:576
	v_lshl_add_u64 v[82:83], v[82:83], 0, v[148:149]
	v_pk_add_f32 v[76:77], v[76:77], v[140:141]
	v_pk_add_f32 v[80:81], v[88:89], v[222:223]
	v_pk_add_f32 v[78:79], v[86:87], v[220:221]
	v_pk_add_f32 v[74:75], v[74:75], v[138:139]
	v_pk_add_f32 v[72:73], v[72:73], v[136:137]
	v_pk_add_f32 v[70:71], v[70:71], v[134:135]
	v_pk_add_f32 v[68:69], v[68:69], v[132:133]
	v_pk_add_f32 v[66:67], v[66:67], v[130:131]
	global_store_dwordx4 v[160:161], v[126:129], off
	global_store_dwordx4 v[160:161], v[122:125], off offset:64
	global_store_dwordx4 v[114:115], v[110:113], off
	global_store_dwordx4 v[114:115], v[106:109], off offset:64
	global_store_dwordx4 v[98:99], v[94:97], off
	global_store_dwordx4 v[98:99], v[90:93], off offset:64
	global_store_dwordx4 v[82:83], v[78:81], off
	global_store_dwordx4 v[82:83], v[74:77], off offset:64
	global_store_dwordx4 v[82:83], v[70:73], off offset:512
	global_store_dwordx4 v[82:83], v[66:69], off offset:576
	s_mov_b64 s[22:23], 0x80000
	v_lshl_add_u64 v[130:131], v[152:153], 0, s[22:23]
	s_mov_b64 s[22:23], 0x90000
	v_lshl_add_u64 v[132:133], v[152:153], 0, s[22:23]
	s_mov_b64 s[22:23], 0xa0000
	v_lshl_add_u64 v[134:135], v[152:153], 0, s[22:23]
	s_mov_b64 s[22:23], 0xb0000
	v_lshl_add_u64 v[136:137], v[152:153], 0, s[22:23]
	v_lshl_add_u64 v[78:79], v[150:151], 0, v[130:131]
	v_lshl_add_u64 v[94:95], v[150:151], 0, v[132:133]
	v_lshl_add_u64 v[110:111], v[150:151], 0, v[134:135]
	v_lshl_add_u64 v[126:127], v[150:151], 0, v[136:137]
	global_load_dwordx4 v[66:69], v[78:79], off
	global_load_dwordx4 v[70:73], v[78:79], off offset:64
	global_load_dwordx4 v[74:77], v[78:79], off offset:512
	v_lshl_add_u64 v[130:131], s[20:21], 0, v[130:131]
	global_load_dwordx4 v[78:81], v[78:79], off offset:576
	s_nop 0
	global_load_dwordx4 v[82:85], v[94:95], off
	global_load_dwordx4 v[86:89], v[94:95], off offset:64
	global_load_dwordx4 v[90:93], v[94:95], off offset:512
	v_lshl_add_u64 v[132:133], s[20:21], 0, v[132:133]
	global_load_dwordx4 v[94:97], v[94:95], off offset:576
	s_nop 0
	global_load_dwordx4 v[98:101], v[110:111], off
	global_load_dwordx4 v[102:105], v[110:111], off offset:64
	global_load_dwordx4 v[106:109], v[110:111], off offset:512
	v_lshl_add_u64 v[134:135], s[20:21], 0, v[134:135]
	global_load_dwordx4 v[110:113], v[110:111], off offset:576
	s_nop 0
	global_load_dwordx4 v[114:117], v[126:127], off
	global_load_dwordx4 v[118:121], v[126:127], off offset:64
	global_load_dwordx4 v[122:125], v[126:127], off offset:512
	s_nop 0
	global_load_dwordx4 v[126:129], v[126:127], off offset:576
	v_lshl_add_u64 v[136:137], s[20:21], 0, v[136:137]
	v_lshl_add_u64 v[130:131], v[130:131], 0, v[148:149]
	v_lshl_add_u64 v[132:133], v[132:133], 0, v[148:149]
	v_lshl_add_u64 v[134:135], v[134:135], 0, v[148:149]
	v_lshl_add_u64 v[136:137], v[136:137], 0, v[148:149]
	s_waitcnt vmcnt(0) lgkmcnt(0)
	v_pk_add_f32 v[64:65], v[64:65], v[68:69]
	v_pk_add_f32 v[62:63], v[62:63], v[66:67]
	v_pk_add_f32 v[60:61], v[60:61], v[72:73]
	v_pk_add_f32 v[58:59], v[58:59], v[70:71]
	v_pk_add_f32 v[44:45], v[44:45], v[76:77]
	v_pk_add_f32 v[42:43], v[42:43], v[74:75]
	v_pk_add_f32 v[36:37], v[36:37], v[80:81]
	v_pk_add_f32 v[34:35], v[34:35], v[78:79]
	v_pk_add_f32 v[56:57], v[56:57], v[84:85]
	v_pk_add_f32 v[54:55], v[54:55], v[82:83]
	v_pk_add_f32 v[52:53], v[52:53], v[88:89]
	v_pk_add_f32 v[50:51], v[50:51], v[86:87]
	v_pk_add_f32 v[28:29], v[28:29], v[92:93]
	v_pk_add_f32 v[26:27], v[26:27], v[90:91]
	v_pk_add_f32 v[24:25], v[24:25], v[96:97]
	v_pk_add_f32 v[22:23], v[22:23], v[94:95]
	v_pk_add_f32 v[48:49], v[48:49], v[100:101]
	v_pk_add_f32 v[46:47], v[46:47], v[98:99]
	v_pk_add_f32 v[40:41], v[40:41], v[104:105]
	v_pk_add_f32 v[38:39], v[38:39], v[102:103]
	v_pk_add_f32 v[14:15], v[14:15], v[108:109]
	v_pk_add_f32 v[12:13], v[12:13], v[106:107]
	v_pk_add_f32 v[10:11], v[10:11], v[112:113]
	v_pk_add_f32 v[8:9], v[8:9], v[110:111]
	v_pk_add_f32 v[32:33], v[32:33], v[116:117]
	v_pk_add_f32 v[30:31], v[30:31], v[114:115]
	v_pk_add_f32 v[20:21], v[20:21], v[120:121]
	v_pk_add_f32 v[18:19], v[18:19], v[118:119]
	v_pk_add_f32 v[6:7], v[6:7], v[124:125]
	v_pk_add_f32 v[4:5], v[4:5], v[122:123]
	v_pk_add_f32 v[2:3], v[2:3], v[128:129]
	v_pk_add_f32 v[0:1], v[0:1], v[126:127]
	global_store_dwordx4 v[130:131], v[62:65], off
	global_store_dwordx4 v[130:131], v[58:61], off offset:64
	global_store_dwordx4 v[130:131], v[42:45], off offset:512
	global_store_dwordx4 v[130:131], v[34:37], off offset:576
	global_store_dwordx4 v[132:133], v[54:57], off
	global_store_dwordx4 v[132:133], v[50:53], off offset:64
	global_store_dwordx4 v[132:133], v[26:29], off offset:512
	global_store_dwordx4 v[132:133], v[22:25], off offset:576
	global_store_dwordx4 v[134:135], v[46:49], off
	global_store_dwordx4 v[134:135], v[38:41], off offset:64
	global_store_dwordx4 v[134:135], v[12:15], off offset:512
	global_store_dwordx4 v[134:135], v[8:11], off offset:576
	global_store_dwordx4 v[136:137], v[30:33], off
	global_store_dwordx4 v[136:137], v[18:21], off offset:64
	global_store_dwordx4 v[136:137], v[4:7], off offset:512
	global_store_dwordx4 v[136:137], v[0:3], off offset:576
	v_readlane_b32 s82, v255, 5
	s_and_b64 vcc, exec, s[38:39]
	s_mov_b32 s2, s4
	s_mov_b32 s18, s8
	s_mov_b64 s[40:41], s[16:17]
	s_mov_b64 s[22:23], s[14:15]
	v_readlane_b32 s83, v255, 6
	s_cbranch_vccz .LBB0_167
	s_waitcnt vmcnt(0)
	s_cmpk_gt_u32 s35, 0xff
	s_cbranch_scc1 .LBB0_178
	s_barrier

.LBB0_211:
	s_add_u32 s18, s16, 0xfffe0080
	s_addc_u32 s19, s17, -1
	s_add_i32 s42, 0, 0x10000
	v_add_u32_e32 v12, s42, v241
	ds_read_b128 v[0:3], v12
	ds_read_b128 v[4:7], v12 offset:1024
	ds_read_b128 v[8:11], v12 offset:2048
	ds_read_b128 v[12:15], v12 offset:3072
	s_cmp_eq_u32 s41, 4
	s_cselect_b32 s23, s2, s19
	s_cselect_b32 s22, s9, s18
	s_cselect_b32 s19, s12, s40
	s_cselect_b32 s18, s15, s34
	v_lshl_add_u64 v[178:179], s[16:17], 0, v[216:217]
	s_add_i32 m0, s52, 0xc000
	ds_read_b128 v[146:149], v243
	ds_read_b128 v[150:153], v243 offset:1024
	ds_read_b128 v[154:157], v243 offset:2048
	ds_read_b128 v[158:161], v243 offset:3072
	ds_read_b128 v[162:165], v243 offset:4096
	ds_read_b128 v[166:169], v243 offset:5120
	ds_read_b128 v[170:173], v243 offset:6144
	ds_read_b128 v[174:177], v243 offset:7168
	global_load_lds_dwordx4 v[178:179], off
	v_lshl_add_u64 v[178:179], s[16:17], 0, v[214:215]
	s_add_i32 m0, s52, 0xe000
	s_nop 0
	global_load_lds_dwordx4 v[178:179], off
	s_waitcnt lgkmcnt(8)
	s_waitcnt vmcnt(10)
	s_barrier
	s_waitcnt lgkmcnt(0)
	s_waitcnt lgkmcnt(0)
	v_mfma_f32_16x16x32_bf16 v[142:145], v[0:3], v[146:149], v[142:145]
	v_mfma_f32_16x16x32_bf16 v[138:141], v[8:11], v[146:149], v[138:141]
	v_mfma_f32_16x16x32_bf16 v[134:137], v[0:3], v[154:157], v[134:137]
	v_mfma_f32_16x16x32_bf16 v[130:133], v[8:11], v[154:157], v[130:133]
	v_mfma_f32_16x16x32_bf16 v[126:129], v[0:3], v[162:165], v[126:129]
	v_mfma_f32_16x16x32_bf16 v[122:125], v[8:11], v[162:165], v[122:125]
	v_mfma_f32_16x16x32_bf16 v[118:121], v[0:3], v[170:173], v[118:121]
	v_mfma_f32_16x16x32_bf16 v[114:117], v[8:11], v[170:173], v[114:117]
	v_mfma_f32_16x16x32_bf16 v[142:145], v[4:7], v[150:153], v[142:145]
	v_mfma_f32_16x16x32_bf16 v[138:141], v[12:15], v[150:153], v[138:141]
	v_mfma_f32_16x16x32_bf16 v[134:137], v[4:7], v[158:161], v[134:137]
	v_mfma_f32_16x16x32_bf16 v[130:133], v[12:15], v[158:161], v[130:133]
	v_mfma_f32_16x16x32_bf16 v[126:129], v[4:7], v[166:169], v[126:129]
	v_mfma_f32_16x16x32_bf16 v[122:125], v[12:15], v[166:169], v[122:125]
	v_mfma_f32_16x16x32_bf16 v[118:121], v[4:7], v[174:177], v[118:121]
	v_mfma_f32_16x16x32_bf16 v[114:117], v[12:15], v[174:177], v[114:117]
	s_barrier
	s_add_i32 s55, 0, 0x14000
	s_add_i32 s42, s42, s49
	v_add_u32_e32 v190, s55, v241
	v_lshl_add_u64 v[194:195], s[18:19], 0, v[16:17]
	s_mov_b32 m0, s42
	ds_read_b128 v[178:181], v190
	ds_read_b128 v[182:185], v190 offset:1024
	ds_read_b128 v[186:189], v190 offset:2048
	ds_read_b128 v[190:193], v190 offset:3072
	global_load_lds_dwordx4 v[194:195], off
	v_lshl_add_u64 v[196:197], s[18:19], 0, v[212:213]
	s_add_i32 m0, s42, 0x2000
	s_nop 0
	global_load_lds_dwordx4 v[196:197], off
	s_waitcnt vmcnt(10)
	s_barrier
	s_waitcnt lgkmcnt(0)
	s_waitcnt lgkmcnt(0)
	v_mfma_f32_16x16x32_bf16 v[110:113], v[178:181], v[146:149], v[110:113]
	v_mfma_f32_16x16x32_bf16 v[106:109], v[186:189], v[146:149], v[106:109]
	v_mfma_f32_16x16x32_bf16 v[102:105], v[178:181], v[154:157], v[102:105]
	v_mfma_f32_16x16x32_bf16 v[98:101], v[186:189], v[154:157], v[98:101]
	v_mfma_f32_16x16x32_bf16 v[94:97], v[178:181], v[162:165], v[94:97]
	v_mfma_f32_16x16x32_bf16 v[90:93], v[186:189], v[162:165], v[90:93]
	v_mfma_f32_16x16x32_bf16 v[86:89], v[178:181], v[170:173], v[86:89]
	v_mfma_f32_16x16x32_bf16 v[82:85], v[186:189], v[170:173], v[82:85]
	v_mfma_f32_16x16x32_bf16 v[110:113], v[182:185], v[150:153], v[110:113]
	v_mfma_f32_16x16x32_bf16 v[106:109], v[190:193], v[150:153], v[106:109]
	v_mfma_f32_16x16x32_bf16 v[102:105], v[182:185], v[158:161], v[102:105]
	v_mfma_f32_16x16x32_bf16 v[98:101], v[190:193], v[158:161], v[98:101]
	v_mfma_f32_16x16x32_bf16 v[94:97], v[182:185], v[166:169], v[94:97]
	v_mfma_f32_16x16x32_bf16 v[90:93], v[190:193], v[166:169], v[90:93]
	v_mfma_f32_16x16x32_bf16 v[86:89], v[182:185], v[174:177], v[86:89]
	v_mfma_f32_16x16x32_bf16 v[82:85], v[190:193], v[174:177], v[82:85]
	s_mov_b32 m0, s52
	v_lshl_add_u64 v[218:219], s[22:23], 0, v[208:209]
	s_barrier
	ds_read_b128 v[146:149], v243 offset:16384
	ds_read_b128 v[150:153], v243 offset:17408
	ds_read_b128 v[154:157], v243 offset:18432
	ds_read_b128 v[158:161], v243 offset:19456
	ds_read_b128 v[162:165], v243 offset:20480
	ds_read_b128 v[166:169], v243 offset:21504
	ds_read_b128 v[170:173], v243 offset:22528
	ds_read_b128 v[174:177], v243 offset:23552
	global_load_lds_dwordx4 v[218:219], off
	v_lshl_add_u64 v[220:221], s[22:23], 0, v[210:211]
	s_mov_b32 m0, s58
	s_nop 0
	global_load_lds_dwordx4 v[220:221], off
	s_barrier
	s_waitcnt lgkmcnt(0)
	s_waitcnt lgkmcnt(0)
	v_mfma_f32_16x16x32_bf16 v[78:81], v[0:3], v[146:149], v[78:81]
	v_mfma_f32_16x16x32_bf16 v[74:77], v[8:11], v[146:149], v[74:77]
	v_mfma_f32_16x16x32_bf16 v[70:73], v[0:3], v[154:157], v[70:73]
	v_mfma_f32_16x16x32_bf16 v[66:69], v[8:11], v[154:157], v[66:69]
	v_mfma_f32_16x16x32_bf16 v[62:65], v[0:3], v[162:165], v[62:65]
	v_mfma_f32_16x16x32_bf16 v[58:61], v[8:11], v[162:165], v[58:61]
	v_mfma_f32_16x16x32_bf16 v[0:3], v[0:3], v[170:173], v[54:57]
	v_mfma_f32_16x16x32_bf16 v[78:81], v[4:7], v[150:153], v[78:81]
	v_mfma_f32_16x16x32_bf16 v[74:77], v[12:15], v[150:153], v[74:77]
	v_mfma_f32_16x16x32_bf16 v[70:73], v[4:7], v[158:161], v[70:73]
	v_mfma_f32_16x16x32_bf16 v[66:69], v[12:15], v[158:161], v[66:69]
	v_mfma_f32_16x16x32_bf16 v[62:65], v[4:7], v[166:169], v[62:65]
	v_mfma_f32_16x16x32_bf16 v[58:61], v[12:15], v[166:169], v[58:61]
	v_mfma_f32_16x16x32_bf16 v[0:3], v[4:7], v[174:177], v[0:3]
	v_mfma_f32_16x16x32_bf16 v[4:7], v[8:11], v[170:173], v[50:53]
	v_mfma_f32_16x16x32_bf16 v[4:7], v[12:15], v[174:177], v[4:7]
	s_barrier
	s_add_u32 s42, s18, 0x20000
	s_addc_u32 s43, s19, 0
	s_add_i32 s55, s55, s49
	v_lshl_add_u64 v[8:9], s[42:43], 0, v[16:17]
	s_mov_b32 m0, s55
	s_nop 0
	global_load_lds_dwordx4 v[8:9], off
	v_lshl_add_u64 v[8:9], s[42:43], 0, v[212:213]
	s_add_i32 m0, s55, 0x2000
	s_nop 0
	global_load_lds_dwordx4 v[8:9], off
	s_waitcnt vmcnt(10)
	s_barrier
	v_mfma_f32_16x16x32_bf16 v[38:41], v[178:181], v[154:157], v[38:41]
	v_mfma_f32_16x16x32_bf16 v[34:37], v[186:189], v[154:157], v[34:37]
	v_mfma_f32_16x16x32_bf16 v[30:33], v[178:181], v[162:165], v[30:33]
	v_mfma_f32_16x16x32_bf16 v[26:29], v[186:189], v[162:165], v[26:29]
	v_mfma_f32_16x16x32_bf16 v[22:25], v[178:181], v[170:173], v[22:25]
	v_mfma_f32_16x16x32_bf16 v[18:21], v[186:189], v[170:173], v[18:21]
	v_mfma_f32_16x16x32_bf16 v[8:11], v[178:181], v[146:149], v[46:49]
	v_mfma_f32_16x16x32_bf16 v[12:15], v[186:189], v[146:149], v[42:45]
	v_mfma_f32_16x16x32_bf16 v[38:41], v[182:185], v[158:161], v[38:41]
	v_mfma_f32_16x16x32_bf16 v[34:37], v[190:193], v[158:161], v[34:37]
	v_mfma_f32_16x16x32_bf16 v[30:33], v[182:185], v[166:169], v[30:33]
	v_mfma_f32_16x16x32_bf16 v[26:29], v[190:193], v[166:169], v[26:29]
	v_mfma_f32_16x16x32_bf16 v[22:25], v[182:185], v[174:177], v[22:25]
	v_mfma_f32_16x16x32_bf16 v[18:21], v[190:193], v[174:177], v[18:21]
	v_mfma_f32_16x16x32_bf16 v[8:11], v[182:185], v[150:153], v[8:11]
	v_mfma_f32_16x16x32_bf16 v[12:15], v[190:193], v[150:153], v[12:15]
	s_add_i32 s42, 0, 0x18000
	v_add_u32_e32 v54, s42, v241
	s_barrier
	ds_read_b128 v[42:45], v54
	ds_read_b128 v[46:49], v54 offset:1024
	ds_read_b128 v[50:53], v54 offset:2048
	ds_read_b128 v[146:149], v54 offset:3072
	s_add_u32 s22, s22, 0x20000
	s_addc_u32 s23, s23, 0
	s_mov_b32 m0, s59
	v_lshl_add_u64 v[178:179], s[22:23], 0, v[208:209]
	ds_read_b128 v[54:57], v243 offset:32768
	ds_read_b128 v[150:153], v243 offset:33792
	ds_read_b128 v[154:157], v243 offset:34816
	ds_read_b128 v[158:161], v243 offset:35840
	ds_read_b128 v[162:165], v243 offset:36864
	ds_read_b128 v[166:169], v243 offset:37888
	ds_read_b128 v[170:173], v243 offset:38912
	ds_read_b128 v[174:177], v243 offset:39936
	global_load_lds_dwordx4 v[178:179], off
	v_lshl_add_u64 v[178:179], s[22:23], 0, v[210:211]
	s_mov_b32 m0, s60
	s_nop 0
	global_load_lds_dwordx4 v[178:179], off
	s_waitcnt lgkmcnt(8)
	s_waitcnt vmcnt(10)
	s_barrier
	s_waitcnt lgkmcnt(0)
	s_waitcnt lgkmcnt(0)
	v_mfma_f32_16x16x32_bf16 v[142:145], v[42:45], v[54:57], v[142:145]
	v_mfma_f32_16x16x32_bf16 v[138:141], v[50:53], v[54:57], v[138:141]
	v_mfma_f32_16x16x32_bf16 v[134:137], v[42:45], v[154:157], v[134:137]
	v_mfma_f32_16x16x32_bf16 v[130:133], v[50:53], v[154:157], v[130:133]
	v_mfma_f32_16x16x32_bf16 v[126:129], v[42:45], v[162:165], v[126:129]
	v_mfma_f32_16x16x32_bf16 v[122:125], v[50:53], v[162:165], v[122:125]
	v_mfma_f32_16x16x32_bf16 v[118:121], v[42:45], v[170:173], v[118:121]
	v_mfma_f32_16x16x32_bf16 v[114:117], v[50:53], v[170:173], v[114:117]
	v_mfma_f32_16x16x32_bf16 v[142:145], v[46:49], v[150:153], v[142:145]
	v_mfma_f32_16x16x32_bf16 v[138:141], v[146:149], v[150:153], v[138:141]
	v_mfma_f32_16x16x32_bf16 v[134:137], v[46:49], v[158:161], v[134:137]
	v_mfma_f32_16x16x32_bf16 v[130:133], v[146:149], v[158:161], v[130:133]
	v_mfma_f32_16x16x32_bf16 v[126:129], v[46:49], v[166:169], v[126:129]
	v_mfma_f32_16x16x32_bf16 v[122:125], v[146:149], v[166:169], v[122:125]
	v_mfma_f32_16x16x32_bf16 v[118:121], v[46:49], v[174:177], v[118:121]
	v_mfma_f32_16x16x32_bf16 v[114:117], v[146:149], v[174:177], v[114:117]
	s_barrier
	s_add_i32 s22, 0, 0x1c000
	s_add_i32 s23, s42, s49
	v_add_u32_e32 v190, s22, v241
	v_lshl_add_u64 v[194:195], v[194:195], 0, s[10:11]
	s_mov_b32 m0, s23
	ds_read_b128 v[178:181], v190
	ds_read_b128 v[182:185], v190 offset:1024
	ds_read_b128 v[186:189], v190 offset:2048
	ds_read_b128 v[190:193], v190 offset:3072
	global_load_lds_dwordx4 v[194:195], off
	v_lshl_add_u64 v[194:195], v[196:197], 0, s[10:11]
	s_add_i32 m0, s23, 0x2000
	s_nop 0
	global_load_lds_dwordx4 v[194:195], off
	s_waitcnt vmcnt(10)
	s_barrier
	s_waitcnt lgkmcnt(0)
	s_waitcnt lgkmcnt(0)
	v_mfma_f32_16x16x32_bf16 v[110:113], v[178:181], v[54:57], v[110:113]
	v_mfma_f32_16x16x32_bf16 v[54:57], v[186:189], v[54:57], v[106:109]
	v_mfma_f32_16x16x32_bf16 v[106:109], v[190:193], v[150:153], v[54:57]
	v_mfma_f32_16x16x32_bf16 v[54:57], v[178:181], v[154:157], v[102:105]
	v_mfma_f32_16x16x32_bf16 v[102:105], v[182:185], v[158:161], v[54:57]
	v_mfma_f32_16x16x32_bf16 v[54:57], v[186:189], v[154:157], v[98:101]
	v_mfma_f32_16x16x32_bf16 v[98:101], v[190:193], v[158:161], v[54:57]
	v_mfma_f32_16x16x32_bf16 v[54:57], v[178:181], v[162:165], v[94:97]
	v_mfma_f32_16x16x32_bf16 v[94:97], v[182:185], v[166:169], v[54:57]
	v_mfma_f32_16x16x32_bf16 v[54:57], v[186:189], v[162:165], v[90:93]
	v_mfma_f32_16x16x32_bf16 v[90:93], v[190:193], v[166:169], v[54:57]
	v_mfma_f32_16x16x32_bf16 v[54:57], v[178:181], v[170:173], v[86:89]
	v_mfma_f32_16x16x32_bf16 v[86:89], v[182:185], v[174:177], v[54:57]
	v_mfma_f32_16x16x32_bf16 v[54:57], v[186:189], v[170:173], v[82:85]
	v_mfma_f32_16x16x32_bf16 v[110:113], v[182:185], v[150:153], v[110:113]
	v_mfma_f32_16x16x32_bf16 v[82:85], v[190:193], v[174:177], v[54:57]
	s_mov_b32 m0, s61
	s_nop 3
	v_lshl_add_u64 v[54:55], v[218:219], 0, s[10:11]
	s_barrier
	ds_read_b128 v[150:153], v243 offset:49152
	ds_read_b128 v[154:157], v243 offset:50176
	ds_read_b128 v[158:161], v243 offset:51200
	ds_read_b128 v[162:165], v243 offset:52224
	ds_read_b128 v[166:169], v243 offset:53248
	ds_read_b128 v[170:173], v243 offset:54272
	ds_read_b128 v[174:177], v243 offset:55296
	ds_read_b128 v[194:197], v243 offset:56320
	global_load_lds_dwordx4 v[54:55], off
	v_lshl_add_u64 v[54:55], v[220:221], 0, s[10:11]
	s_mov_b32 m0, s35
	s_nop 0
	global_load_lds_dwordx4 v[54:55], off
	s_barrier
	s_waitcnt lgkmcnt(0)
	s_waitcnt lgkmcnt(0)
	v_mfma_f32_16x16x32_bf16 v[54:57], v[42:45], v[150:153], v[78:81]
	v_mfma_f32_16x16x32_bf16 v[78:81], v[46:49], v[154:157], v[54:57]
	v_mfma_f32_16x16x32_bf16 v[54:57], v[50:53], v[150:153], v[74:77]
	v_mfma_f32_16x16x32_bf16 v[74:77], v[146:149], v[154:157], v[54:57]
	v_mfma_f32_16x16x32_bf16 v[54:57], v[42:45], v[158:161], v[70:73]
	v_mfma_f32_16x16x32_bf16 v[70:73], v[46:49], v[162:165], v[54:57]
	v_mfma_f32_16x16x32_bf16 v[54:57], v[50:53], v[158:161], v[66:69]
	v_mfma_f32_16x16x32_bf16 v[66:69], v[146:149], v[162:165], v[54:57]
	v_mfma_f32_16x16x32_bf16 v[54:57], v[42:45], v[166:169], v[62:65]
	v_mfma_f32_16x16x32_bf16 v[62:65], v[46:49], v[170:173], v[54:57]
	v_mfma_f32_16x16x32_bf16 v[54:57], v[50:53], v[166:169], v[58:61]
	v_mfma_f32_16x16x32_bf16 v[0:3], v[42:45], v[174:177], v[0:3]
	v_mfma_f32_16x16x32_bf16 v[58:61], v[146:149], v[170:173], v[54:57]
	v_mfma_f32_16x16x32_bf16 v[54:57], v[46:49], v[194:197], v[0:3]
	v_mfma_f32_16x16x32_bf16 v[0:3], v[50:53], v[174:177], v[4:7]
	v_mfma_f32_16x16x32_bf16 v[50:53], v[146:149], v[194:197], v[0:3]
	s_barrier
	s_add_u32 s18, s18, 0x20080
	s_addc_u32 s19, s19, 0
	s_add_i32 s22, s22, s49
	s_nop 1
	v_lshl_add_u64 v[0:1], s[18:19], 0, v[16:17]
	s_mov_b32 m0, s22
	s_nop 0
	global_load_lds_dwordx4 v[0:1], off
	v_lshl_add_u64 v[0:1], s[18:19], 0, v[212:213]
	s_add_i32 m0, s22, 0x2000
	s_nop 0
	global_load_lds_dwordx4 v[0:1], off
	s_waitcnt vmcnt(10)
	s_barrier
	v_mfma_f32_16x16x32_bf16 v[0:3], v[178:181], v[150:153], v[8:11]
	v_mfma_f32_16x16x32_bf16 v[46:49], v[182:185], v[154:157], v[0:3]
	v_mfma_f32_16x16x32_bf16 v[0:3], v[186:189], v[150:153], v[12:15]
	v_mfma_f32_16x16x32_bf16 v[42:45], v[190:193], v[154:157], v[0:3]
	v_mfma_f32_16x16x32_bf16 v[0:3], v[178:181], v[158:161], v[38:41]
	v_mfma_f32_16x16x32_bf16 v[38:41], v[182:185], v[162:165], v[0:3]
	v_mfma_f32_16x16x32_bf16 v[0:3], v[186:189], v[158:161], v[34:37]
	v_mfma_f32_16x16x32_bf16 v[34:37], v[190:193], v[162:165], v[0:3]
	v_mfma_f32_16x16x32_bf16 v[0:3], v[178:181], v[166:169], v[30:33]
	v_mfma_f32_16x16x32_bf16 v[30:33], v[182:185], v[170:173], v[0:3]
	v_mfma_f32_16x16x32_bf16 v[0:3], v[186:189], v[166:169], v[26:29]
	v_mfma_f32_16x16x32_bf16 v[26:29], v[190:193], v[170:173], v[0:3]
	v_mfma_f32_16x16x32_bf16 v[0:3], v[178:181], v[174:177], v[22:25]
	v_mfma_f32_16x16x32_bf16 v[22:25], v[182:185], v[194:197], v[0:3]
	v_mfma_f32_16x16x32_bf16 v[0:3], v[186:189], v[174:177], v[18:21]
	v_mfma_f32_16x16x32_bf16 v[18:21], v[190:193], v[194:197], v[0:3]
	s_add_i32 s41, s41, 2
	s_add_u32 s34, s34, 0x100
	s_addc_u32 s40, s40, 0
	s_add_u32 s16, s16, 0x100
	s_addc_u32 s17, s17, 0
	s_cmp_gt_u32 s41, 5
	s_barrier
	s_cbranch_scc0 .LBB0_211
	s_cmp_eq_u32 s84, 3
	s_cselect_b64 s[16:17], -1, 0
	s_cmp_lg_u32 s84, 3
	v_lshl_add_u32 v220, s8, 8, v240
	v_lshl_or_b32 v218, s14, 8, v242
	s_cselect_b64 s[8:9], -1, 0
	s_lshl_b32 s14, s84, 10
	v_mov_b64_e32 v[0:1], s[94:95]
	s_ashr_i32 s15, s14, 31
	v_mad_i64_i32 v[0:1], s[18:19], v220, s66, v[0:1]
	v_ashrrev_i32_e32 v219, 31, v218
	v_lshl_add_u64 v[0:1], s[14:15], 1, v[0:1]
	v_lshl_add_u64 v[4:5], v[218:219], 1, v[0:1]
	v_add_co_u32_e32 v0, vcc, 0x2000, v4
	s_mov_b64 s[18:19], 0x2400
	s_nop 0
	v_addc_co_u32_e32 v1, vcc, 0, v5, vcc
	global_load_dwordx4 v[0:3], v[0:1], off offset:1024
	s_and_b64 vcc, exec, s[16:17]
	v_lshl_add_u64 v[4:5], v[4:5], 0, s[18:19]
	s_cbranch_vccnz .LBB0_214
	global_load_dwordx4 v[12:15], v[4:5], off offset:2048

.LBB0_979:
	s_add_u32 s22, s20, 0xfffc0080
	s_addc_u32 s23, s21, -1
	s_add_i32 s61, 0, 0x10000
	v_add_u32_e32 v144, s61, v147
	ds_read_b128 v[140:143], v144
	ds_read_b128 v[150:153], v144 offset:1024
	ds_read_b128 v[154:157], v144 offset:2048
	ds_read_b128 v[158:161], v144 offset:3072
	s_cmp_eq_u32 s60, 12
	s_cselect_b32 s29, s9, s23
	s_cselect_b32 s28, s56, s22
	s_cselect_b32 s23, s5, s59
	s_cselect_b32 s22, s57, s58
	v_lshl_add_u64 v[144:145], s[20:21], 0, v[138:139]
	s_add_i32 m0, s12, 0xc000
	ds_read_b128 v[162:165], v149
	ds_read_b128 v[166:169], v149 offset:1024
	ds_read_b128 v[170:173], v149 offset:2048
	ds_read_b128 v[174:177], v149 offset:3072
	ds_read_b128 v[178:181], v149 offset:4096
	ds_read_b128 v[182:185], v149 offset:5120
	ds_read_b128 v[186:189], v149 offset:6144
	ds_read_b128 v[190:193], v149 offset:7168
	global_load_lds_dwordx4 v[144:145], off
	v_lshl_add_u64 v[144:145], s[20:21], 0, v[136:137]
	s_add_i32 m0, s12, 0xe000
	s_nop 0
	global_load_lds_dwordx4 v[144:145], off
	s_waitcnt lgkmcnt(8)
	s_waitcnt vmcnt(10)
	s_barrier
	s_waitcnt lgkmcnt(0)
	s_waitcnt lgkmcnt(0)
	v_mfma_f32_16x16x32_bf16 v[78:81], v[140:143], v[162:165], v[78:81]
	v_mfma_f32_16x16x32_bf16 v[74:77], v[154:157], v[162:165], v[74:77]
	v_mfma_f32_16x16x32_bf16 v[70:73], v[140:143], v[170:173], v[70:73]
	v_mfma_f32_16x16x32_bf16 v[66:69], v[154:157], v[170:173], v[66:69]
	v_mfma_f32_16x16x32_bf16 v[62:65], v[140:143], v[178:181], v[62:65]
	v_mfma_f32_16x16x32_bf16 v[54:57], v[154:157], v[178:181], v[54:57]
	v_mfma_f32_16x16x32_bf16 v[50:53], v[140:143], v[186:189], v[50:53]
	v_mfma_f32_16x16x32_bf16 v[42:45], v[154:157], v[186:189], v[42:45]
	v_mfma_f32_16x16x32_bf16 v[78:81], v[150:153], v[166:169], v[78:81]
	v_mfma_f32_16x16x32_bf16 v[74:77], v[158:161], v[166:169], v[74:77]
	v_mfma_f32_16x16x32_bf16 v[70:73], v[150:153], v[174:177], v[70:73]
	v_mfma_f32_16x16x32_bf16 v[66:69], v[158:161], v[174:177], v[66:69]
	v_mfma_f32_16x16x32_bf16 v[62:65], v[150:153], v[182:185], v[62:65]
	v_mfma_f32_16x16x32_bf16 v[54:57], v[158:161], v[182:185], v[54:57]
	v_mfma_f32_16x16x32_bf16 v[50:53], v[150:153], v[190:193], v[50:53]
	v_mfma_f32_16x16x32_bf16 v[42:45], v[158:161], v[190:193], v[42:45]
	s_barrier
	s_add_i32 s79, 0, 0x14000
	v_add_u32_e32 v144, s79, v147
	s_add_i32 s61, s61, s48
	ds_read_b128 v[194:197], v144
	ds_read_b128 v[208:211], v144 offset:1024
	ds_read_b128 v[212:215], v144 offset:2048
	ds_read_b128 v[216:219], v144 offset:3072
	v_lshl_add_u64 v[144:145], s[22:23], 0, v[16:17]
	s_mov_b32 m0, s61
	v_lshl_add_u64 v[220:221], s[22:23], 0, v[130:131]
	global_load_lds_dwordx4 v[144:145], off
	s_add_i32 m0, s61, 0x2000
	s_nop 0
	global_load_lds_dwordx4 v[220:221], off
	s_waitcnt vmcnt(10)
	s_barrier
	s_waitcnt lgkmcnt(0)
	s_waitcnt lgkmcnt(0)
	v_mfma_f32_16x16x32_bf16 v[126:129], v[194:197], v[162:165], v[126:129]
	v_mfma_f32_16x16x32_bf16 v[122:125], v[212:215], v[162:165], v[122:125]
	v_mfma_f32_16x16x32_bf16 v[118:121], v[194:197], v[170:173], v[118:121]
	v_mfma_f32_16x16x32_bf16 v[114:117], v[212:215], v[170:173], v[114:117]
	v_mfma_f32_16x16x32_bf16 v[110:113], v[194:197], v[178:181], v[110:113]
	v_mfma_f32_16x16x32_bf16 v[106:109], v[212:215], v[178:181], v[106:109]
	v_mfma_f32_16x16x32_bf16 v[102:105], v[194:197], v[186:189], v[102:105]
	v_mfma_f32_16x16x32_bf16 v[98:101], v[212:215], v[186:189], v[98:101]
	v_mfma_f32_16x16x32_bf16 v[126:129], v[208:211], v[166:169], v[126:129]
	v_mfma_f32_16x16x32_bf16 v[122:125], v[216:219], v[166:169], v[122:125]
	v_mfma_f32_16x16x32_bf16 v[118:121], v[208:211], v[174:177], v[118:121]
	v_mfma_f32_16x16x32_bf16 v[114:117], v[216:219], v[174:177], v[114:117]
	v_mfma_f32_16x16x32_bf16 v[110:113], v[208:211], v[182:185], v[110:113]
	v_mfma_f32_16x16x32_bf16 v[106:109], v[216:219], v[182:185], v[106:109]
	v_mfma_f32_16x16x32_bf16 v[102:105], v[208:211], v[190:193], v[102:105]
	v_mfma_f32_16x16x32_bf16 v[98:101], v[216:219], v[190:193], v[98:101]
	s_mov_b32 m0, s12
	v_lshl_add_u64 v[222:223], s[28:29], 0, v[134:135]
	s_barrier
	ds_read_b128 v[162:165], v149 offset:16384
	ds_read_b128 v[166:169], v149 offset:17408
	ds_read_b128 v[170:173], v149 offset:18432
	ds_read_b128 v[174:177], v149 offset:19456
	ds_read_b128 v[178:181], v149 offset:20480
	ds_read_b128 v[182:185], v149 offset:21504
	ds_read_b128 v[186:189], v149 offset:22528
	ds_read_b128 v[190:193], v149 offset:23552
	global_load_lds_dwordx4 v[222:223], off
	v_lshl_add_u64 v[224:225], s[28:29], 0, v[132:133]
	s_mov_b32 m0, s34
	s_nop 0
	global_load_lds_dwordx4 v[224:225], off
	s_barrier
	s_waitcnt lgkmcnt(0)
	s_waitcnt lgkmcnt(0)
	v_mfma_f32_16x16x32_bf16 v[34:37], v[140:143], v[162:165], v[34:37]
	v_mfma_f32_16x16x32_bf16 v[30:33], v[154:157], v[162:165], v[30:33]
	v_mfma_f32_16x16x32_bf16 v[22:25], v[140:143], v[170:173], v[22:25]
	v_mfma_f32_16x16x32_bf16 v[18:21], v[154:157], v[170:173], v[18:21]
	v_mfma_f32_16x16x32_bf16 v[12:15], v[140:143], v[178:181], v[12:15]
	v_mfma_f32_16x16x32_bf16 v[8:11], v[154:157], v[178:181], v[8:11]
	v_mfma_f32_16x16x32_bf16 v[4:7], v[140:143], v[186:189], v[4:7]
	v_mfma_f32_16x16x32_bf16 v[0:3], v[154:157], v[186:189], v[0:3]
	v_mfma_f32_16x16x32_bf16 v[34:37], v[150:153], v[166:169], v[34:37]
	v_mfma_f32_16x16x32_bf16 v[30:33], v[158:161], v[166:169], v[30:33]
	v_mfma_f32_16x16x32_bf16 v[22:25], v[150:153], v[174:177], v[22:25]
	v_mfma_f32_16x16x32_bf16 v[18:21], v[158:161], v[174:177], v[18:21]
	v_mfma_f32_16x16x32_bf16 v[12:15], v[150:153], v[182:185], v[12:15]
	v_mfma_f32_16x16x32_bf16 v[8:11], v[158:161], v[182:185], v[8:11]
	v_mfma_f32_16x16x32_bf16 v[4:7], v[150:153], v[190:193], v[4:7]
	v_mfma_f32_16x16x32_bf16 v[0:3], v[158:161], v[190:193], v[0:3]
	s_barrier
	s_add_u32 s82, s22, 0x40000
	s_addc_u32 s83, s23, 0
	s_add_i32 s61, s79, s48
	v_lshl_add_u64 v[140:141], s[82:83], 0, v[16:17]
	s_mov_b32 m0, s61
	s_nop 0
	global_load_lds_dwordx4 v[140:141], off
	v_lshl_add_u64 v[140:141], s[82:83], 0, v[130:131]
	s_add_i32 m0, s61, 0x2000
	s_nop 0
	global_load_lds_dwordx4 v[140:141], off
	s_waitcnt vmcnt(10)
	s_barrier
	v_mfma_f32_16x16x32_bf16 v[94:97], v[194:197], v[162:165], v[94:97]
	v_mfma_f32_16x16x32_bf16 v[90:93], v[212:215], v[162:165], v[90:93]
	v_mfma_f32_16x16x32_bf16 v[86:89], v[194:197], v[170:173], v[86:89]
	v_mfma_f32_16x16x32_bf16 v[82:85], v[212:215], v[170:173], v[82:85]
	v_mfma_f32_16x16x32_bf16 v[58:61], v[194:197], v[178:181], v[58:61]
	v_mfma_f32_16x16x32_bf16 v[46:49], v[212:215], v[178:181], v[46:49]
	v_mfma_f32_16x16x32_bf16 v[38:41], v[194:197], v[186:189], v[38:41]
	v_mfma_f32_16x16x32_bf16 v[26:29], v[212:215], v[186:189], v[26:29]
	v_mfma_f32_16x16x32_bf16 v[94:97], v[208:211], v[166:169], v[94:97]
	v_mfma_f32_16x16x32_bf16 v[90:93], v[216:219], v[166:169], v[90:93]
	v_mfma_f32_16x16x32_bf16 v[86:89], v[208:211], v[174:177], v[86:89]
	v_mfma_f32_16x16x32_bf16 v[82:85], v[216:219], v[174:177], v[82:85]
	v_mfma_f32_16x16x32_bf16 v[58:61], v[208:211], v[182:185], v[58:61]
	v_mfma_f32_16x16x32_bf16 v[46:49], v[216:219], v[182:185], v[46:49]
	v_mfma_f32_16x16x32_bf16 v[38:41], v[208:211], v[190:193], v[38:41]
	v_mfma_f32_16x16x32_bf16 v[26:29], v[216:219], v[190:193], v[26:29]
	s_add_i32 s61, 0, 0x18000
	v_add_u32_e32 v158, s61, v147
	s_barrier
	ds_read_b128 v[140:143], v158
	ds_read_b128 v[150:153], v158 offset:1024
	ds_read_b128 v[154:157], v158 offset:2048
	ds_read_b128 v[158:161], v158 offset:3072
	s_add_u32 s28, s28, 0x40000
	s_addc_u32 s29, s29, 0
	s_mov_b32 m0, s49
	v_lshl_add_u64 v[194:195], s[28:29], 0, v[134:135]
	ds_read_b128 v[162:165], v149 offset:32768
	ds_read_b128 v[166:169], v149 offset:33792
	ds_read_b128 v[170:173], v149 offset:34816
	ds_read_b128 v[174:177], v149 offset:35840
	ds_read_b128 v[178:181], v149 offset:36864
	ds_read_b128 v[182:185], v149 offset:37888
	ds_read_b128 v[186:189], v149 offset:38912
	ds_read_b128 v[190:193], v149 offset:39936
	global_load_lds_dwordx4 v[194:195], off
	v_lshl_add_u64 v[194:195], s[28:29], 0, v[132:133]
	s_mov_b32 m0, s50
	s_nop 0
	global_load_lds_dwordx4 v[194:195], off
	s_waitcnt lgkmcnt(8)
	s_waitcnt vmcnt(10)
	s_barrier
	s_waitcnt lgkmcnt(0)
	s_waitcnt lgkmcnt(0)
	v_mfma_f32_16x16x32_bf16 v[78:81], v[140:143], v[162:165], v[78:81]
	v_mfma_f32_16x16x32_bf16 v[74:77], v[154:157], v[162:165], v[74:77]
	v_mfma_f32_16x16x32_bf16 v[70:73], v[140:143], v[170:173], v[70:73]
	v_mfma_f32_16x16x32_bf16 v[66:69], v[154:157], v[170:173], v[66:69]
	v_mfma_f32_16x16x32_bf16 v[62:65], v[140:143], v[178:181], v[62:65]
	v_mfma_f32_16x16x32_bf16 v[54:57], v[154:157], v[178:181], v[54:57]
	v_mfma_f32_16x16x32_bf16 v[50:53], v[140:143], v[186:189], v[50:53]
	v_mfma_f32_16x16x32_bf16 v[42:45], v[154:157], v[186:189], v[42:45]
	v_mfma_f32_16x16x32_bf16 v[78:81], v[150:153], v[166:169], v[78:81]
	v_mfma_f32_16x16x32_bf16 v[74:77], v[158:161], v[166:169], v[74:77]
	v_mfma_f32_16x16x32_bf16 v[70:73], v[150:153], v[174:177], v[70:73]
	v_mfma_f32_16x16x32_bf16 v[66:69], v[158:161], v[174:177], v[66:69]
	v_mfma_f32_16x16x32_bf16 v[62:65], v[150:153], v[182:185], v[62:65]
	v_mfma_f32_16x16x32_bf16 v[54:57], v[158:161], v[182:185], v[54:57]
	v_mfma_f32_16x16x32_bf16 v[50:53], v[150:153], v[190:193], v[50:53]
	v_mfma_f32_16x16x32_bf16 v[42:45], v[158:161], v[190:193], v[42:45]
	s_barrier
	s_add_i32 s28, 0, 0x1c000
	s_add_i32 s29, s61, s48
	v_add_u32_e32 v216, s28, v147
	v_lshl_add_u64 v[144:145], v[144:145], 0, s[10:11]
	s_mov_b32 m0, s29
	ds_read_b128 v[194:197], v216
	ds_read_b128 v[208:211], v216 offset:1024
	ds_read_b128 v[212:215], v216 offset:2048
	ds_read_b128 v[216:219], v216 offset:3072
	global_load_lds_dwordx4 v[144:145], off
	v_lshl_add_u64 v[144:145], v[220:221], 0, s[10:11]
	s_add_i32 m0, s29, 0x2000
	s_nop 0
	global_load_lds_dwordx4 v[144:145], off
	s_waitcnt vmcnt(10)
	s_barrier
	s_waitcnt lgkmcnt(0)
	s_waitcnt lgkmcnt(0)
	v_mfma_f32_16x16x32_bf16 v[126:129], v[194:197], v[162:165], v[126:129]
	v_mfma_f32_16x16x32_bf16 v[122:125], v[212:215], v[162:165], v[122:125]
	v_mfma_f32_16x16x32_bf16 v[118:121], v[194:197], v[170:173], v[118:121]
	v_mfma_f32_16x16x32_bf16 v[114:117], v[212:215], v[170:173], v[114:117]
	v_mfma_f32_16x16x32_bf16 v[110:113], v[194:197], v[178:181], v[110:113]
	v_mfma_f32_16x16x32_bf16 v[106:109], v[212:215], v[178:181], v[106:109]
	v_mfma_f32_16x16x32_bf16 v[102:105], v[194:197], v[186:189], v[102:105]
	v_mfma_f32_16x16x32_bf16 v[98:101], v[212:215], v[186:189], v[98:101]
	v_mfma_f32_16x16x32_bf16 v[126:129], v[208:211], v[166:169], v[126:129]
	v_mfma_f32_16x16x32_bf16 v[122:125], v[216:219], v[166:169], v[122:125]
	v_mfma_f32_16x16x32_bf16 v[118:121], v[208:211], v[174:177], v[118:121]
	v_mfma_f32_16x16x32_bf16 v[114:117], v[216:219], v[174:177], v[114:117]
	v_mfma_f32_16x16x32_bf16 v[110:113], v[208:211], v[182:185], v[110:113]
	v_mfma_f32_16x16x32_bf16 v[106:109], v[216:219], v[182:185], v[106:109]
	v_mfma_f32_16x16x32_bf16 v[102:105], v[208:211], v[190:193], v[102:105]
	v_mfma_f32_16x16x32_bf16 v[98:101], v[216:219], v[190:193], v[98:101]
	s_mov_b32 m0, s51
	v_lshl_add_u64 v[144:145], v[222:223], 0, s[10:11]
	s_barrier
	ds_read_b128 v[162:165], v149 offset:49152
	ds_read_b128 v[166:169], v149 offset:50176
	ds_read_b128 v[170:173], v149 offset:51200
	ds_read_b128 v[174:177], v149 offset:52224
	ds_read_b128 v[178:181], v149 offset:53248
	ds_read_b128 v[182:185], v149 offset:54272
	ds_read_b128 v[186:189], v149 offset:55296
	ds_read_b128 v[190:193], v149 offset:56320
	global_load_lds_dwordx4 v[144:145], off
	v_lshl_add_u64 v[144:145], v[224:225], 0, s[10:11]
	s_mov_b32 m0, s52
	s_nop 0
	global_load_lds_dwordx4 v[144:145], off
	s_barrier
	s_waitcnt lgkmcnt(0)
	s_waitcnt lgkmcnt(0)
	v_mfma_f32_16x16x32_bf16 v[34:37], v[140:143], v[162:165], v[34:37]
	v_mfma_f32_16x16x32_bf16 v[30:33], v[154:157], v[162:165], v[30:33]
	v_mfma_f32_16x16x32_bf16 v[22:25], v[140:143], v[170:173], v[22:25]
	v_mfma_f32_16x16x32_bf16 v[18:21], v[154:157], v[170:173], v[18:21]
	v_mfma_f32_16x16x32_bf16 v[12:15], v[140:143], v[178:181], v[12:15]
	v_mfma_f32_16x16x32_bf16 v[8:11], v[154:157], v[178:181], v[8:11]
	v_mfma_f32_16x16x32_bf16 v[4:7], v[140:143], v[186:189], v[4:7]
	v_mfma_f32_16x16x32_bf16 v[0:3], v[154:157], v[186:189], v[0:3]
	v_mfma_f32_16x16x32_bf16 v[34:37], v[150:153], v[166:169], v[34:37]
	v_mfma_f32_16x16x32_bf16 v[30:33], v[158:161], v[166:169], v[30:33]
	v_mfma_f32_16x16x32_bf16 v[22:25], v[150:153], v[174:177], v[22:25]
	v_mfma_f32_16x16x32_bf16 v[18:21], v[158:161], v[174:177], v[18:21]
	v_mfma_f32_16x16x32_bf16 v[12:15], v[150:153], v[182:185], v[12:15]
	v_mfma_f32_16x16x32_bf16 v[8:11], v[158:161], v[182:185], v[8:11]
	v_mfma_f32_16x16x32_bf16 v[4:7], v[150:153], v[190:193], v[4:7]
	v_mfma_f32_16x16x32_bf16 v[0:3], v[158:161], v[190:193], v[0:3]
	s_barrier
	s_add_u32 s22, s22, 0x40080
	s_addc_u32 s23, s23, 0
	s_add_i32 s28, s28, s48
	v_lshl_add_u64 v[140:141], s[22:23], 0, v[16:17]
	s_mov_b32 m0, s28
	s_nop 0
	global_load_lds_dwordx4 v[140:141], off
	v_lshl_add_u64 v[140:141], s[22:23], 0, v[130:131]
	s_add_i32 m0, s28, 0x2000
	s_nop 0
	global_load_lds_dwordx4 v[140:141], off
	s_waitcnt vmcnt(10)
	s_barrier
	v_mfma_f32_16x16x32_bf16 v[94:97], v[194:197], v[162:165], v[94:97]
	v_mfma_f32_16x16x32_bf16 v[90:93], v[212:215], v[162:165], v[90:93]
	v_mfma_f32_16x16x32_bf16 v[86:89], v[194:197], v[170:173], v[86:89]
	v_mfma_f32_16x16x32_bf16 v[82:85], v[212:215], v[170:173], v[82:85]
	v_mfma_f32_16x16x32_bf16 v[58:61], v[194:197], v[178:181], v[58:61]
	v_mfma_f32_16x16x32_bf16 v[46:49], v[212:215], v[178:181], v[46:49]
	v_mfma_f32_16x16x32_bf16 v[38:41], v[194:197], v[186:189], v[38:41]
	v_mfma_f32_16x16x32_bf16 v[26:29], v[212:215], v[186:189], v[26:29]
	v_mfma_f32_16x16x32_bf16 v[94:97], v[208:211], v[166:169], v[94:97]
	v_mfma_f32_16x16x32_bf16 v[90:93], v[216:219], v[166:169], v[90:93]
	v_mfma_f32_16x16x32_bf16 v[86:89], v[208:211], v[174:177], v[86:89]
	v_mfma_f32_16x16x32_bf16 v[82:85], v[216:219], v[174:177], v[82:85]
	v_mfma_f32_16x16x32_bf16 v[58:61], v[208:211], v[182:185], v[58:61]
	v_mfma_f32_16x16x32_bf16 v[46:49], v[216:219], v[182:185], v[46:49]
	v_mfma_f32_16x16x32_bf16 v[38:41], v[208:211], v[190:193], v[38:41]
	v_mfma_f32_16x16x32_bf16 v[26:29], v[216:219], v[190:193], v[26:29]
	s_add_i32 s60, s60, 2
	s_add_u32 s58, s58, 0x100
	s_addc_u32 s59, s59, 0
	s_add_u32 s20, s20, 0x100
	s_addc_u32 s21, s21, 0
	s_cmp_gt_u32 s60, 13
	s_barrier
	s_cbranch_scc0 .LBB0_979
	v_lshl_or_b32 v144, s19, 8, v148
	v_lshl_add_u32 v140, s18, 8, v146
	v_ashrrev_i32_e32 v145, 31, v144
	v_mov_b64_e32 v[142:143], s[94:95]
	v_mad_i64_i32 v[150:151], s[20:21], v140, s66, v[142:143]
	v_lshlrev_b64 v[144:145], 1, v[144:145]
	v_lshl_add_u64 v[154:155], v[150:151], 0, v[144:145]
	v_cvt_pk_bf16_f32 v150, v78, v79
	v_cvt_pk_bf16_f32 v151, v80, v81
	v_cvt_pk_bf16_f32 v152, v74, v75
	v_cvt_pk_bf16_f32 v153, v76, v77
	global_store_dwordx4 v[154:155], v[150:153], off
	v_cvt_pk_bf16_f32 v126, v126, v127
	v_cvt_pk_bf16_f32 v127, v128, v129
	v_cvt_pk_bf16_f32 v128, v122, v123
	v_cvt_pk_bf16_f32 v129, v124, v125
	global_store_dwordx4 v[154:155], v[126:129], off offset:256
	v_or_b32_e32 v122, 16, v140
	v_mad_i64_i32 v[124:125], s[20:21], v122, s66, v[142:143]
	v_lshl_add_u64 v[128:129], v[124:125], 0, v[144:145]
	v_cvt_pk_bf16_f32 v124, v70, v71
	v_cvt_pk_bf16_f32 v125, v72, v73
	v_cvt_pk_bf16_f32 v126, v66, v67
	v_cvt_pk_bf16_f32 v127, v68, v69
	global_store_dwordx4 v[128:129], v[124:127], off
	v_cvt_pk_bf16_f32 v118, v118, v119
	v_cvt_pk_bf16_f32 v119, v120, v121
	v_cvt_pk_bf16_f32 v120, v114, v115
	v_cvt_pk_bf16_f32 v121, v116, v117
	global_store_dwordx4 v[128:129], v[118:121], off offset:256
	v_or_b32_e32 v114, 32, v140
	v_mad_i64_i32 v[116:117], s[20:21], v114, s66, v[142:143]
	v_lshl_add_u64 v[120:121], v[116:117], 0, v[144:145]
	v_cvt_pk_bf16_f32 v116, v62, v63
	v_cvt_pk_bf16_f32 v117, v64, v65
	v_cvt_pk_bf16_f32 v118, v54, v55
	v_cvt_pk_bf16_f32 v119, v56, v57
	global_store_dwordx4 v[120:121], v[116:119], off
	v_cvt_pk_bf16_f32 v110, v110, v111
	v_cvt_pk_bf16_f32 v111, v112, v113
	v_cvt_pk_bf16_f32 v112, v106, v107
	v_cvt_pk_bf16_f32 v113, v108, v109
	global_store_dwordx4 v[120:121], v[110:113], off offset:256
	v_or_b32_e32 v106, 48, v140
	v_mad_i64_i32 v[108:109], s[20:21], v106, s66, v[142:143]
	v_lshl_add_u64 v[112:113], v[108:109], 0, v[144:145]
	v_cvt_pk_bf16_f32 v108, v50, v51
	v_cvt_pk_bf16_f32 v109, v52, v53
	v_cvt_pk_bf16_f32 v110, v42, v43
	v_cvt_pk_bf16_f32 v111, v44, v45
	global_store_dwordx4 v[112:113], v[108:111], off
	v_cvt_pk_bf16_f32 v102, v102, v103
	v_cvt_pk_bf16_f32 v103, v104, v105
	v_cvt_pk_bf16_f32 v104, v98, v99
	v_cvt_pk_bf16_f32 v105, v100, v101
	global_store_dwordx4 v[112:113], v[102:105], off offset:256
	v_add_u32_e32 v98, 0x80, v140
	v_mad_i64_i32 v[100:101], s[20:21], v98, s66, v[142:143]
	v_lshl_add_u64 v[104:105], v[100:101], 0, v[144:145]
	v_cvt_pk_bf16_f32 v100, v34, v35
	v_cvt_pk_bf16_f32 v101, v36, v37
	v_cvt_pk_bf16_f32 v102, v30, v31
	v_cvt_pk_bf16_f32 v103, v32, v33
	global_store_dwordx4 v[104:105], v[100:103], off
	v_cvt_pk_bf16_f32 v94, v94, v95
	v_cvt_pk_bf16_f32 v95, v96, v97
	v_cvt_pk_bf16_f32 v96, v90, v91
	v_cvt_pk_bf16_f32 v97, v92, v93
	global_store_dwordx4 v[104:105], v[94:97], off offset:256
	v_add_u32_e32 v90, 0x90, v140
	v_mad_i64_i32 v[92:93], s[20:21], v90, s66, v[142:143]
	v_lshl_add_u64 v[96:97], v[92:93], 0, v[144:145]
	v_cvt_pk_bf16_f32 v92, v22, v23
	v_cvt_pk_bf16_f32 v93, v24, v25
	v_cvt_pk_bf16_f32 v94, v18, v19
	v_cvt_pk_bf16_f32 v95, v20, v21
	global_store_dwordx4 v[96:97], v[92:95], off
	v_cvt_pk_bf16_f32 v86, v86, v87
	v_cvt_pk_bf16_f32 v87, v88, v89
	v_cvt_pk_bf16_f32 v88, v82, v83
	v_cvt_pk_bf16_f32 v89, v84, v85
	global_store_dwordx4 v[96:97], v[86:89], off offset:256
	v_add_u32_e32 v82, 0xa0, v140
	v_mad_i64_i32 v[84:85], s[20:21], v82, s66, v[142:143]
	v_lshl_add_u64 v[88:89], v[84:85], 0, v[144:145]
	v_cvt_pk_bf16_f32 v84, v12, v13
	v_cvt_pk_bf16_f32 v85, v14, v15
	v_cvt_pk_bf16_f32 v86, v8, v9
	v_cvt_pk_bf16_f32 v87, v10, v11
	global_store_dwordx4 v[88:89], v[84:87], off
	v_cvt_pk_bf16_f32 v58, v58, v59
	v_cvt_pk_bf16_f32 v59, v60, v61
	v_cvt_pk_bf16_f32 v60, v46, v47
	v_cvt_pk_bf16_f32 v61, v48, v49
	global_store_dwordx4 v[88:89], v[58:61], off offset:256
	v_add_u32_e32 v46, 0xb0, v140
	v_mad_i64_i32 v[48:49], s[20:21], v46, s66, v[142:143]
	v_lshl_add_u64 v[48:49], v[48:49], 0, v[144:145]
	v_cvt_pk_bf16_f32 v58, v4, v5
	v_cvt_pk_bf16_f32 v59, v6, v7
	v_cvt_pk_bf16_f32 v60, v0, v1
	v_cvt_pk_bf16_f32 v61, v2, v3
	global_store_dwordx4 v[48:49], v[58:61], off
	v_cvt_pk_bf16_f32 v38, v38, v39
	v_cvt_pk_bf16_f32 v39, v40, v41
	v_cvt_pk_bf16_f32 v40, v26, v27
	v_cvt_pk_bf16_f32 v41, v28, v29
	global_store_dwordx4 v[48:49], v[38:41], off offset:256
	s_cmp_eq_u32 s19, 34
	s_cselect_b64 s[18:19], -1, 0
	s_and_b64 s[20:21], s[38:39], s[18:19]
	s_and_saveexec_b64 s[18:19], s[20:21]
	s_cbranch_execz .LBB0_975
	v_ashrrev_i32_e32 v141, 31, v140
	v_lshlrev_b64 v[26:27], 5, v[140:141]
	v_ashrrev_i32_e32 v123, 31, v122
	v_lshl_add_u64 v[26:27], s[42:43], 0, v[26:27]
	global_store_dwordx4 v[26:27], v[78:81], off
	global_store_dwordx4 v[26:27], v[74:77], off offset:16
	v_lshlrev_b64 v[26:27], 5, v[122:123]
	v_ashrrev_i32_e32 v115, 31, v114
	v_lshl_add_u64 v[26:27], s[42:43], 0, v[26:27]
	global_store_dwordx4 v[26:27], v[70:73], off
	global_store_dwordx4 v[26:27], v[66:69], off offset:16
	v_lshlrev_b64 v[26:27], 5, v[114:115]
	v_ashrrev_i32_e32 v107, 31, v106
	v_lshl_add_u64 v[26:27], s[42:43], 0, v[26:27]
	global_store_dwordx4 v[26:27], v[62:65], off
	global_store_dwordx4 v[26:27], v[54:57], off offset:16
	v_lshlrev_b64 v[26:27], 5, v[106:107]
	v_ashrrev_i32_e32 v99, 31, v98
	v_lshl_add_u64 v[26:27], s[42:43], 0, v[26:27]
	global_store_dwordx4 v[26:27], v[50:53], off
	global_store_dwordx4 v[26:27], v[42:45], off offset:16
	v_lshlrev_b64 v[26:27], 5, v[98:99]
	v_ashrrev_i32_e32 v91, 31, v90
	v_lshl_add_u64 v[26:27], s[42:43], 0, v[26:27]
	global_store_dwordx4 v[26:27], v[34:37], off
	global_store_dwordx4 v[26:27], v[30:33], off offset:16
	v_lshlrev_b64 v[26:27], 5, v[90:91]
	v_ashrrev_i32_e32 v83, 31, v82
	v_lshl_add_u64 v[26:27], s[42:43], 0, v[26:27]
	global_store_dwordx4 v[26:27], v[22:25], off
	global_store_dwordx4 v[26:27], v[18:21], off offset:16
	v_ashrrev_i32_e32 v47, 31, v46
	s_nop 0
	v_lshlrev_b64 v[18:19], 5, v[82:83]
	v_lshl_add_u64 v[18:19], s[42:43], 0, v[18:19]
	global_store_dwordx4 v[18:19], v[12:15], off
	global_store_dwordx4 v[18:19], v[8:11], off offset:16
	s_nop 1
	v_lshlrev_b64 v[8:9], 5, v[46:47]
	v_lshl_add_u64 v[8:9], s[42:43], 0, v[8:9]
	global_store_dwordx4 v[8:9], v[4:7], off
	global_store_dwordx4 v[8:9], v[0:3], off offset:16
	s_branch .LBB0_975
